# w_mo / w_down GEMM phases: the residual tile for the RMW epilogue is fetched into the freed LDS stage buffers (LDS-DMA) during the last K-loop body; epilogue reads 14 of 16 H pieces from LDS
# speedup vs baseline: 1.0088x; 1.0058x over previous
.LBB0_4:
	v_readlane_b32 s0, v254, 0
	v_readlane_b32 s1, v254, 1
	s_add_u32 s58, s0, 0x118
	s_addc_u32 s59, s1, 0
	s_add_u32 s0, s68, 0x1bd08000
	v_writelane_b32 v254, s0, 4
	s_addc_u32 s0, s69, 0
	s_add_u32 s60, s68, 0x1bd08200
	s_addc_u32 s61, s69, 0
	s_add_u32 s62, s68, 0x1bd08400
	s_addc_u32 s63, s69, 0
	s_add_u32 s64, s68, 0x1bd08500
	s_addc_u32 s65, s69, 0
	s_add_u32 s66, s68, 0x1bd08600
	s_addc_u32 s67, s69, 0
	s_add_u32 s72, s68, 0x1bd08700
	s_addc_u32 s73, s69, 0
	s_add_u32 s74, s68, 0x1bd08800
	s_addc_u32 s75, s69, 0
	s_add_u32 s76, s68, 0x1bd08900
	s_addc_u32 s77, s69, 0
	s_add_u32 s78, s68, 0x1bd08a00
	s_addc_u32 s79, s69, 0
	s_add_u32 s86, s68, 0x1bd08b00
	s_addc_u32 s87, s69, 0
	s_add_u32 s88, s68, 0x1bd08c00
	s_addc_u32 s89, s69, 0
	s_add_u32 s90, s68, 0x1bd08d00
	s_addc_u32 s91, s69, 0
	s_add_u32 s92, s68, 0x1bd08e00
	s_addc_u32 s93, s69, 0
	s_add_u32 s94, s68, 0x1bd08f00
	s_addc_u32 s95, s69, 0
	s_add_u32 s96, s68, 0x1bd09000
	s_addc_u32 s97, s69, 0
	s_add_u32 s50, s68, 0x1bd09100
	s_addc_u32 s51, s69, 0
	s_add_u32 s52, s68, 0x1bd09200
	s_addc_u32 s53, s69, 0
	s_add_u32 s80, s68, 0x1bd09300
	s_addc_u32 s81, s69, 0
	v_writelane_b32 v254, s0, 5
	s_add_u32 s0, s68, 0x1bd0b400
	s_addc_u32 s1, s69, 0
	v_writelane_b32 v254, s0, 6
	v_mbcnt_lo_u32_b32 v1, -1, 0
	s_movk_i32 s55, 0x4200
	v_writelane_b32 v254, s1, 7
	s_add_u32 s0, s68, 0x1bd0b500
	s_addc_u32 s1, s69, 0
	v_writelane_b32 v254, s0, 8
	v_mov_b32_e32 v26, 0
	v_mov_b32_e32 v172, 0x358637bd
	v_writelane_b32 v254, s1, 9
	s_add_i32 s0, 0, 0x16000
	v_writelane_b32 v254, s0, 10
	s_add_i32 s0, 0, 0x11000
	v_writelane_b32 v254, s0, 11
	s_add_i32 s0, 0, 0x13800
	v_writelane_b32 v254, s0, 12
	s_add_i32 s0, 0, 0x18800
	v_writelane_b32 v254, s0, 13
	s_add_i32 s0, 0, 0x18a00
	v_writelane_b32 v254, s0, 14
	s_add_i32 s0, 0, 0x189fc
	v_writelane_b32 v254, s0, 15
	s_add_i32 s0, 0, 0x22004
	v_writelane_b32 v254, s0, 16
	s_mov_b32 s1, 0
	v_writelane_b32 v254, s0, 17
	s_movk_i32 s49, 0x41ff
	s_movk_i32 s68, 0x7f0
	v_writelane_b32 v254, s1, 18
	v_writelane_b32 v254, s54, 19
	v_writelane_b32 v254, s58, 20
	s_movk_i32 s69, 0x5000
	s_mov_b32 s82, 0xb000
	v_writelane_b32 v254, s59, 21
	v_writelane_b32 v254, s60, 22
	s_mov_b32 s83, 0xd000
	s_movk_i32 s84, 0x5800
	v_writelane_b32 v254, s61, 23
	v_writelane_b32 v254, s62, 24
	s_movk_i32 s85, 0x7fd
	v_mov_b32_e32 v173, 0x2000
	v_writelane_b32 v254, s63, 25
	v_writelane_b32 v254, s64, 26
	v_mov_b32_e32 v228, 1
	v_mov_b32_e32 v229, 0x4000
	v_writelane_b32 v254, s65, 27
	v_writelane_b32 v254, s66, 28
	v_mbcnt_hi_u32_b32 v230, -1, v1
	v_mov_b32_e32 v231, 0x7f800000
	v_writelane_b32 v254, s67, 29
	v_writelane_b32 v254, s72, 30
	s_mov_b64 s[56:57], 0xb000
	s_mov_b64 s[16:17], 0x80
	v_writelane_b32 v254, s73, 31
	v_writelane_b32 v254, s74, 32
	s_mov_b64 s[20:21], 0x100
	s_nop 0
	v_writelane_b32 v254, s75, 33
	v_writelane_b32 v254, s76, 34
	s_nop 1
	v_writelane_b32 v254, s77, 35
	v_writelane_b32 v254, s78, 36
	s_nop 1
	v_writelane_b32 v254, s79, 37
	v_writelane_b32 v254, s86, 38
	s_nop 1
	v_writelane_b32 v254, s87, 39
	v_writelane_b32 v254, s88, 40
	s_nop 1
	v_writelane_b32 v254, s89, 41
	v_writelane_b32 v254, s90, 42
	s_nop 1
	v_writelane_b32 v254, s91, 43
	v_writelane_b32 v254, s92, 44
	s_nop 1
	v_writelane_b32 v254, s93, 45
	v_writelane_b32 v254, s94, 46
	s_nop 1
	v_writelane_b32 v254, s95, 47
	v_writelane_b32 v254, s96, 48
	s_nop 1
	v_writelane_b32 v254, s97, 49
	v_writelane_b32 v254, s50, 50
	s_nop 1
	v_writelane_b32 v254, s51, 51
	v_writelane_b32 v254, s52, 52
	s_nop 1
	v_writelane_b32 v254, s53, 53
	v_writelane_b32 v254, s80, 54
	s_nop 1
	v_writelane_b32 v254, s81, 55
	s_mov_b32 s32, 0
	s_branch .LBB0_6

.LBB0_894:
	s_add_i32 s6, s2, 2
	s_add_u32 s7, s64, s0
	s_addc_u32 s3, s65, s1
	s_add_u32 s8, s66, s0
	s_addc_u32 s9, s67, s1
	s_add_i32 s33, 0, 0x10000
	v_add_u32_e32 v160, s33, v165
	ds_read_b128 v[148:151], v160
	ds_read_b128 v[152:155], v160 offset:1024
	ds_read_b128 v[156:159], v160 offset:2048
	ds_read_b128 v[160:163], v160 offset:3072
	s_cmp_eq_u32 s92, s2
	s_cselect_b32 s2, s72, s7
	s_cselect_b32 s3, s73, s3
	s_cselect_b32 s9, s75, s9
	s_cselect_b32 s8, s74, s8
	s_cbranch_scc0 .Lhp_skip
	s_cmp_lg_u64 s[70:71], 0
	s_cbranch_scc1 .Lhp_skip
	s_cmp_eq_u32 s63, 7
	s_cbranch_scc1 .Lhp_on
	s_cmp_lg_u32 s63, 9
	s_cbranch_scc1 .Lhp_skip
.Lhp_on:
	s_mov_b32 s32, 1
	v_add_u32_e32 v143, v168, v167
	v_lshlrev_b32_e32 v142, 11, v166
	s_lshl_b32 s72, s81, 11
	s_lshl_b32 s73, s62, 1
	v_lshl_add_u32 v142, v143, 1, v142
	s_add_u32 s72, s72, s73
	s_add_u32 s72, s46, s72
	s_addc_u32 s73, s47, 0
.Lhp_skip:
	v_lshl_add_u64 v[232:233], s[64:65], 0, v[132:133]
	s_add_i32 m0, s84, 0xc000
	ds_read_b128 v[196:199], v195
	ds_read_b128 v[200:203], v195 offset:1024
	ds_read_b128 v[204:207], v195 offset:2048
	ds_read_b128 v[208:211], v195 offset:3072
	ds_read_b128 v[212:215], v195 offset:4096
	ds_read_b128 v[216:219], v195 offset:5120
	ds_read_b128 v[220:223], v195 offset:6144
	ds_read_b128 v[224:227], v195 offset:7168
	global_load_lds_dwordx4 v[232:233], off
	v_lshl_add_u64 v[232:233], s[64:65], 0, v[134:135]
	s_add_i32 m0, s84, 0xe000
	s_nop 0
	global_load_lds_dwordx4 v[232:233], off
	s_waitcnt lgkmcnt(8)
	s_barrier
	s_waitcnt lgkmcnt(0)
	s_setprio 1
	s_waitcnt lgkmcnt(0)
	v_mfma_f32_16x16x32_bf16 v[128:131], v[148:151], v[196:199], v[128:131]
	v_mfma_f32_16x16x32_bf16 v[124:127], v[156:159], v[196:199], v[124:127]
	v_mfma_f32_16x16x32_bf16 v[108:111], v[148:151], v[204:207], v[108:111]
	v_mfma_f32_16x16x32_bf16 v[100:103], v[156:159], v[204:207], v[100:103]
	v_mfma_f32_16x16x32_bf16 v[88:91], v[148:151], v[212:215], v[88:91]
	v_mfma_f32_16x16x32_bf16 v[84:87], v[156:159], v[212:215], v[84:87]
	v_mfma_f32_16x16x32_bf16 v[56:59], v[148:151], v[220:223], v[56:59]
	v_mfma_f32_16x16x32_bf16 v[44:47], v[156:159], v[220:223], v[44:47]
	v_mfma_f32_16x16x32_bf16 v[128:131], v[152:155], v[200:203], v[128:131]
	v_mfma_f32_16x16x32_bf16 v[124:127], v[160:163], v[200:203], v[124:127]
	v_mfma_f32_16x16x32_bf16 v[108:111], v[152:155], v[208:211], v[108:111]
	v_mfma_f32_16x16x32_bf16 v[100:103], v[160:163], v[208:211], v[100:103]
	v_mfma_f32_16x16x32_bf16 v[88:91], v[152:155], v[216:219], v[88:91]
	v_mfma_f32_16x16x32_bf16 v[84:87], v[160:163], v[216:219], v[84:87]
	v_mfma_f32_16x16x32_bf16 v[56:59], v[152:155], v[224:227], v[56:59]
	v_mfma_f32_16x16x32_bf16 v[44:47], v[160:163], v[224:227], v[44:47]
	s_setprio 0
	s_barrier
	s_add_i32 s7, 0, 0x14000
	s_add_i32 s33, s33, s87
	v_lshl_add_u64 v[248:249], s[8:9], 0, v[138:139]
	s_add_u32 s8, s8, s34
	v_add_u32_e32 v244, s7, v165
	s_mov_b32 m0, s33
	s_addc_u32 s9, s9, s35
	ds_read_b128 v[232:235], v244
	ds_read_b128 v[236:239], v244 offset:1024
	ds_read_b128 v[240:243], v244 offset:2048
	ds_read_b128 v[244:247], v244 offset:3072
	s_cmp_eq_u32 s32, 0
	s_cbranch_scc1 .Lhp_o3
	global_load_lds_dwordx4 v142, s[72:73]
	s_add_u32 s72, s72, 0x100
	s_addc_u32 s73, s73, 0
	s_branch .Lhp_e3
.Lhp_o3:
	global_load_lds_dwordx4 v[248:249], off
.Lhp_e3:
	v_lshl_add_u64 v[250:251], s[8:9], 0, v[138:139]
	s_add_i32 m0, s33, 0x2000
	s_nop 0
	s_cmp_eq_u32 s32, 0
	s_cbranch_scc1 .Lhp_o4
	global_load_lds_dwordx4 v142, s[72:73]
	s_add_u32 s72, s72, 0x7f00
	s_addc_u32 s73, s73, 0
	s_branch .Lhp_e4
.Lhp_o4:
	global_load_lds_dwordx4 v[250:251], off
.Lhp_e4:
	s_waitcnt vmcnt(10)
	s_barrier
	s_waitcnt lgkmcnt(0)
	s_setprio 1
	s_waitcnt lgkmcnt(0)
	v_mfma_f32_16x16x32_bf16 v[120:123], v[232:235], v[196:199], v[120:123]
	v_mfma_f32_16x16x32_bf16 v[116:119], v[240:243], v[196:199], v[116:119]
	v_mfma_f32_16x16x32_bf16 v[112:115], v[232:235], v[204:207], v[112:115]
	v_mfma_f32_16x16x32_bf16 v[104:107], v[240:243], v[204:207], v[104:107]
	v_mfma_f32_16x16x32_bf16 v[96:99], v[232:235], v[212:215], v[96:99]
	v_mfma_f32_16x16x32_bf16 v[92:95], v[240:243], v[212:215], v[92:95]
	v_mfma_f32_16x16x32_bf16 v[80:83], v[232:235], v[220:223], v[80:83]
	v_mfma_f32_16x16x32_bf16 v[76:79], v[240:243], v[220:223], v[76:79]
	v_mfma_f32_16x16x32_bf16 v[120:123], v[236:239], v[200:203], v[120:123]
	v_mfma_f32_16x16x32_bf16 v[116:119], v[244:247], v[200:203], v[116:119]
	v_mfma_f32_16x16x32_bf16 v[112:115], v[236:239], v[208:211], v[112:115]
	v_mfma_f32_16x16x32_bf16 v[104:107], v[244:247], v[208:211], v[104:107]
	v_mfma_f32_16x16x32_bf16 v[96:99], v[236:239], v[216:219], v[96:99]
	v_mfma_f32_16x16x32_bf16 v[92:95], v[244:247], v[216:219], v[92:95]
	v_mfma_f32_16x16x32_bf16 v[80:83], v[236:239], v[224:227], v[80:83]
	v_mfma_f32_16x16x32_bf16 v[76:79], v[244:247], v[224:227], v[76:79]
	s_setprio 0
	s_add_u32 s76, s2, s30
	s_mov_b32 m0, s84
	v_lshl_add_u64 v[250:251], s[2:3], 0, v[140:141]
	s_addc_u32 s77, s3, s31
	s_barrier
	ds_read_b128 v[196:199], v195 offset:16384
	ds_read_b128 v[200:203], v195 offset:17408
	ds_read_b128 v[204:207], v195 offset:18432
	ds_read_b128 v[208:211], v195 offset:19456
	ds_read_b128 v[212:215], v195 offset:20480
	ds_read_b128 v[216:219], v195 offset:21504
	ds_read_b128 v[220:223], v195 offset:22528
	ds_read_b128 v[224:227], v195 offset:23552
	s_cmp_eq_u32 s32, 0
	s_cbranch_scc1 .Lhp_o5
	global_load_lds_dwordx4 v142, s[72:73]
	s_add_u32 s72, s72, 0x100
	s_addc_u32 s73, s73, 0
	s_branch .Lhp_e5

.Lhp_e5:
	v_lshl_add_u64 v[252:253], s[76:77], 0, v[140:141]
	s_mov_b32 m0, s93
	s_nop 0
	s_cmp_eq_u32 s32, 0
	s_cbranch_scc1 .Lhp_o6
	global_load_lds_dwordx4 v142, s[72:73]
	s_add_u32 s72, s72, 0x7f00
	s_addc_u32 s73, s73, 0
	s_branch .Lhp_e6
.Lhp_o6:
	global_load_lds_dwordx4 v[252:253], off
.Lhp_e6:
	s_barrier
	s_waitcnt lgkmcnt(0)
	s_setprio 1
	s_waitcnt lgkmcnt(0)
	v_mfma_f32_16x16x32_bf16 v[64:67], v[148:151], v[196:199], v[64:67]
	v_mfma_f32_16x16x32_bf16 v[60:63], v[156:159], v[196:199], v[60:63]
	v_mfma_f32_16x16x32_bf16 v[40:43], v[148:151], v[204:207], v[40:43]
	v_mfma_f32_16x16x32_bf16 v[36:39], v[156:159], v[204:207], v[36:39]
	v_mfma_f32_16x16x32_bf16 v[22:25], v[148:151], v[212:215], v[22:25]
	v_mfma_f32_16x16x32_bf16 v[18:21], v[156:159], v[212:215], v[18:21]
	v_mfma_f32_16x16x32_bf16 v[6:9], v[148:151], v[220:223], v[6:9]
	v_mfma_f32_16x16x32_bf16 v[2:5], v[156:159], v[220:223], v[2:5]
	v_mfma_f32_16x16x32_bf16 v[64:67], v[152:155], v[200:203], v[64:67]
	v_mfma_f32_16x16x32_bf16 v[60:63], v[160:163], v[200:203], v[60:63]
	v_mfma_f32_16x16x32_bf16 v[40:43], v[152:155], v[208:211], v[40:43]
	v_mfma_f32_16x16x32_bf16 v[36:39], v[160:163], v[208:211], v[36:39]
	v_mfma_f32_16x16x32_bf16 v[22:25], v[152:155], v[216:219], v[22:25]
	v_mfma_f32_16x16x32_bf16 v[18:21], v[160:163], v[216:219], v[18:21]
	v_mfma_f32_16x16x32_bf16 v[6:9], v[152:155], v[224:227], v[6:9]
	v_mfma_f32_16x16x32_bf16 v[2:5], v[160:163], v[224:227], v[2:5]
	s_setprio 0
	s_barrier
	s_add_u32 s2, s8, s34
	s_addc_u32 s3, s9, s35
	s_add_i32 s7, s7, s87
	s_add_u32 s8, s2, s34
	v_lshl_add_u64 v[148:149], s[2:3], 0, v[138:139]
	s_mov_b32 m0, s7
	s_addc_u32 s9, s3, s35
	s_cmp_eq_u32 s32, 0
	s_cbranch_scc1 .Lhp_o7
	global_load_lds_dwordx4 v142, s[72:73]
	s_add_u32 s72, s72, 0x100
	s_addc_u32 s73, s73, 0
	s_branch .Lhp_e7
.Lhp_o7:
	global_load_lds_dwordx4 v[148:149], off
.Lhp_e7:
	v_lshl_add_u64 v[252:253], s[8:9], 0, v[138:139]
	s_add_i32 m0, s7, 0x2000
	s_nop 0
	s_cmp_eq_u32 s32, 0
	s_cbranch_scc1 .Lhp_o8
	global_load_lds_dwordx4 v142, s[72:73]
	s_add_u32 s72, s72, 0x7f00
	s_addc_u32 s73, s73, 0
	s_branch .Lhp_e8

.Lhp_e8:
	s_waitcnt vmcnt(8)
	s_barrier
	s_setprio 1
	v_mfma_f32_16x16x32_bf16 v[72:75], v[232:235], v[196:199], v[72:75]
	v_mfma_f32_16x16x32_bf16 v[68:71], v[240:243], v[196:199], v[68:71]
	v_mfma_f32_16x16x32_bf16 v[52:55], v[232:235], v[204:207], v[52:55]
	v_mfma_f32_16x16x32_bf16 v[48:51], v[240:243], v[204:207], v[48:51]
	v_mfma_f32_16x16x32_bf16 v[32:35], v[232:235], v[212:215], v[32:35]
	v_mfma_f32_16x16x32_bf16 v[28:31], v[240:243], v[212:215], v[28:31]
	v_mfma_f32_16x16x32_bf16 v[14:17], v[232:235], v[220:223], v[14:17]
	v_mfma_f32_16x16x32_bf16 v[10:13], v[240:243], v[220:223], v[10:13]
	v_mfma_f32_16x16x32_bf16 v[72:75], v[236:239], v[200:203], v[72:75]
	v_mfma_f32_16x16x32_bf16 v[68:71], v[244:247], v[200:203], v[68:71]
	v_mfma_f32_16x16x32_bf16 v[52:55], v[236:239], v[208:211], v[52:55]
	v_mfma_f32_16x16x32_bf16 v[48:51], v[244:247], v[208:211], v[48:51]
	v_mfma_f32_16x16x32_bf16 v[32:35], v[236:239], v[216:219], v[32:35]
	v_mfma_f32_16x16x32_bf16 v[28:31], v[244:247], v[216:219], v[28:31]
	v_mfma_f32_16x16x32_bf16 v[14:17], v[236:239], v[224:227], v[14:17]
	v_mfma_f32_16x16x32_bf16 v[10:13], v[244:247], v[224:227], v[10:13]
	s_setprio 0
	s_add_i32 s7, 0, 0x18000
	v_add_u32_e32 v160, s7, v165
	s_barrier
	ds_read_b128 v[148:151], v160
	ds_read_b128 v[152:155], v160 offset:1024
	ds_read_b128 v[156:159], v160 offset:2048
	ds_read_b128 v[160:163], v160 offset:3072
	s_add_u32 s8, s76, s30
	s_addc_u32 s9, s77, s31
	s_add_u32 s76, s8, s30
	s_mov_b32 m0, s28
	v_lshl_add_u64 v[232:233], s[8:9], 0, v[140:141]
	s_addc_u32 s77, s9, s31
	ds_read_b128 v[196:199], v195 offset:32768
	ds_read_b128 v[200:203], v195 offset:33792
	ds_read_b128 v[204:207], v195 offset:34816
	ds_read_b128 v[208:211], v195 offset:35840
	ds_read_b128 v[212:215], v195 offset:36864
	ds_read_b128 v[216:219], v195 offset:37888
	ds_read_b128 v[220:223], v195 offset:38912
	ds_read_b128 v[224:227], v195 offset:39936
	s_cmp_eq_u32 s32, 0
	s_cbranch_scc1 .Lhp_o9
	global_load_lds_dwordx4 v142, s[72:73]
	s_add_u32 s72, s72, 0x100
	s_addc_u32 s73, s73, 0
	s_branch .Lhp_e9
.Lhp_o9:
	global_load_lds_dwordx4 v[232:233], off
.Lhp_e9:
	v_lshl_add_u64 v[232:233], s[76:77], 0, v[140:141]
	s_mov_b32 m0, s29
	s_nop 0
	s_cmp_eq_u32 s32, 0
	s_cbranch_scc1 .Lhp_o10
	global_load_lds_dwordx4 v142, s[72:73]
	s_add_u32 s72, s72, 0x27f00
	s_addc_u32 s73, s73, 0
	s_branch .Lhp_e10

.Lhp_e10:
	s_waitcnt lgkmcnt(8)
	s_barrier
	s_waitcnt lgkmcnt(0)
	s_setprio 1
	s_waitcnt lgkmcnt(0)
	v_mfma_f32_16x16x32_bf16 v[128:131], v[148:151], v[196:199], v[128:131]
	v_mfma_f32_16x16x32_bf16 v[124:127], v[156:159], v[196:199], v[124:127]
	v_mfma_f32_16x16x32_bf16 v[108:111], v[148:151], v[204:207], v[108:111]
	v_mfma_f32_16x16x32_bf16 v[100:103], v[156:159], v[204:207], v[100:103]
	v_mfma_f32_16x16x32_bf16 v[88:91], v[148:151], v[212:215], v[88:91]
	v_mfma_f32_16x16x32_bf16 v[84:87], v[156:159], v[212:215], v[84:87]
	v_mfma_f32_16x16x32_bf16 v[56:59], v[148:151], v[220:223], v[56:59]
	v_mfma_f32_16x16x32_bf16 v[44:47], v[156:159], v[220:223], v[44:47]
	v_mfma_f32_16x16x32_bf16 v[128:131], v[152:155], v[200:203], v[128:131]
	v_mfma_f32_16x16x32_bf16 v[124:127], v[160:163], v[200:203], v[124:127]
	v_mfma_f32_16x16x32_bf16 v[108:111], v[152:155], v[208:211], v[108:111]
	v_mfma_f32_16x16x32_bf16 v[100:103], v[160:163], v[208:211], v[100:103]
	v_mfma_f32_16x16x32_bf16 v[88:91], v[152:155], v[216:219], v[88:91]
	v_mfma_f32_16x16x32_bf16 v[84:87], v[160:163], v[216:219], v[84:87]
	v_mfma_f32_16x16x32_bf16 v[56:59], v[152:155], v[224:227], v[56:59]
	v_mfma_f32_16x16x32_bf16 v[44:47], v[160:163], v[224:227], v[44:47]
	s_setprio 0
	s_barrier
	s_add_i32 s33, 0, 0x1c000
	s_add_i32 s7, s7, s87
	s_add_u32 s2, s2, s94
	v_add_u32_e32 v244, s33, v165
	v_lshl_add_u64 v[248:249], v[248:249], 0, s[16:17]
	s_mov_b32 m0, s7
	s_addc_u32 s3, s3, s95
	ds_read_b128 v[232:235], v244
	ds_read_b128 v[236:239], v244 offset:1024
	ds_read_b128 v[240:243], v244 offset:2048
	ds_read_b128 v[244:247], v244 offset:3072
	s_cmp_eq_u32 s32, 0
	s_cbranch_scc1 .Lhp_o11
	global_load_lds_dwordx4 v142, s[72:73]
	s_add_u32 s72, s72, 0x100
	s_addc_u32 s73, s73, 0
	s_branch .Lhp_e11

.Lhp_e11:
	v_lshl_add_u64 v[248:249], s[2:3], 0, v[138:139]
	v_lshl_add_u64 v[248:249], v[248:249], 0, s[16:17]
	s_add_i32 m0, s7, 0x2000
	s_nop 0
	s_cmp_eq_u32 s32, 0
	s_cbranch_scc1 .Lhp_o12
	global_load_lds_dwordx4 v142, s[72:73]
	s_add_u32 s72, s72, 0x7f00
	s_addc_u32 s73, s73, 0
	s_branch .Lhp_e12

.Lhp_e12:
	s_waitcnt vmcnt(10)
	s_barrier
	s_waitcnt lgkmcnt(0)
	s_setprio 1
	s_waitcnt lgkmcnt(0)
	v_mfma_f32_16x16x32_bf16 v[120:123], v[232:235], v[196:199], v[120:123]
	v_mfma_f32_16x16x32_bf16 v[116:119], v[240:243], v[196:199], v[116:119]
	v_mfma_f32_16x16x32_bf16 v[112:115], v[232:235], v[204:207], v[112:115]
	v_mfma_f32_16x16x32_bf16 v[104:107], v[240:243], v[204:207], v[104:107]
	v_mfma_f32_16x16x32_bf16 v[96:99], v[232:235], v[212:215], v[96:99]
	v_mfma_f32_16x16x32_bf16 v[92:95], v[240:243], v[212:215], v[92:95]
	v_mfma_f32_16x16x32_bf16 v[80:83], v[232:235], v[220:223], v[80:83]
	v_mfma_f32_16x16x32_bf16 v[76:79], v[240:243], v[220:223], v[76:79]
	v_mfma_f32_16x16x32_bf16 v[120:123], v[236:239], v[200:203], v[120:123]
	v_mfma_f32_16x16x32_bf16 v[116:119], v[244:247], v[200:203], v[116:119]
	v_mfma_f32_16x16x32_bf16 v[112:115], v[236:239], v[208:211], v[112:115]
	v_mfma_f32_16x16x32_bf16 v[104:107], v[244:247], v[208:211], v[104:107]
	v_mfma_f32_16x16x32_bf16 v[96:99], v[236:239], v[216:219], v[96:99]
	v_mfma_f32_16x16x32_bf16 v[92:95], v[244:247], v[216:219], v[92:95]
	v_mfma_f32_16x16x32_bf16 v[80:83], v[236:239], v[224:227], v[80:83]
	v_mfma_f32_16x16x32_bf16 v[76:79], v[244:247], v[224:227], v[76:79]
	s_setprio 0
	s_add_u32 s8, s8, s96
	s_mov_b32 m0, s40
	v_lshl_add_u64 v[248:249], v[250:251], 0, s[16:17]
	s_addc_u32 s9, s9, s97
	s_barrier
	ds_read_b128 v[196:199], v195 offset:49152
	ds_read_b128 v[200:203], v195 offset:50176
	ds_read_b128 v[204:207], v195 offset:51200
	ds_read_b128 v[208:211], v195 offset:52224
	ds_read_b128 v[212:215], v195 offset:53248
	ds_read_b128 v[216:219], v195 offset:54272
	ds_read_b128 v[220:223], v195 offset:55296
	ds_read_b128 v[224:227], v195 offset:56320
	s_cmp_eq_u32 s32, 0
	s_cbranch_scc1 .Lhp_o13
	global_load_lds_dwordx4 v142, s[72:73]
	s_add_u32 s72, s72, 0x100
	s_addc_u32 s73, s73, 0
	s_branch .Lhp_e13

.Lhp_e13:
	v_lshl_add_u64 v[248:249], s[8:9], 0, v[140:141]
	v_lshl_add_u64 v[248:249], v[248:249], 0, s[16:17]
	s_mov_b32 m0, s41
	s_nop 0
	s_cmp_eq_u32 s32, 0
	s_cbranch_scc1 .Lhp_o14
	global_load_lds_dwordx4 v142, s[72:73]
	s_add_u32 s72, s72, 0x7f00
	s_addc_u32 s73, s73, 0
	s_branch .Lhp_e14

.Lhp_e14:
	s_barrier
	s_waitcnt lgkmcnt(0)
	s_setprio 1
	s_waitcnt lgkmcnt(0)
	v_mfma_f32_16x16x32_bf16 v[64:67], v[148:151], v[196:199], v[64:67]
	v_mfma_f32_16x16x32_bf16 v[60:63], v[156:159], v[196:199], v[60:63]
	v_mfma_f32_16x16x32_bf16 v[40:43], v[148:151], v[204:207], v[40:43]
	v_mfma_f32_16x16x32_bf16 v[36:39], v[156:159], v[204:207], v[36:39]
	v_mfma_f32_16x16x32_bf16 v[22:25], v[148:151], v[212:215], v[22:25]
	v_mfma_f32_16x16x32_bf16 v[18:21], v[156:159], v[212:215], v[18:21]
	v_mfma_f32_16x16x32_bf16 v[6:9], v[148:151], v[220:223], v[6:9]
	v_mfma_f32_16x16x32_bf16 v[2:5], v[156:159], v[220:223], v[2:5]
	v_mfma_f32_16x16x32_bf16 v[64:67], v[152:155], v[200:203], v[64:67]
	v_mfma_f32_16x16x32_bf16 v[60:63], v[160:163], v[200:203], v[60:63]
	v_mfma_f32_16x16x32_bf16 v[40:43], v[152:155], v[208:211], v[40:43]
	v_mfma_f32_16x16x32_bf16 v[36:39], v[160:163], v[208:211], v[36:39]
	v_mfma_f32_16x16x32_bf16 v[22:25], v[152:155], v[216:219], v[22:25]
	v_mfma_f32_16x16x32_bf16 v[18:21], v[160:163], v[216:219], v[18:21]
	v_mfma_f32_16x16x32_bf16 v[6:9], v[152:155], v[224:227], v[6:9]
	v_mfma_f32_16x16x32_bf16 v[2:5], v[160:163], v[224:227], v[2:5]
	s_setprio 0
	s_barrier
	s_add_u32 s2, s2, s34
	s_addc_u32 s3, s3, s35
	v_lshl_add_u64 v[148:149], s[2:3], 0, v[138:139]
	s_add_i32 s2, s33, s87
	v_lshl_add_u64 v[148:149], v[148:149], 0, s[16:17]
	s_mov_b32 m0, s2
	s_nop 0
	s_cmp_eq_u32 s32, 0
	s_cbranch_scc1 .Lhp_o15
	global_load_lds_dwordx4 v142, s[72:73]
	s_add_u32 s72, s72, 0x100
	s_addc_u32 s73, s73, 0
	s_branch .Lhp_e15

.Lhp_e15:
	v_lshl_add_u64 v[148:149], v[252:253], 0, s[16:17]
	s_add_i32 m0, s2, 0x2000
	s_nop 0
	s_cmp_eq_u32 s32, 0
	s_cbranch_scc1 .Lhp_o16
	global_load_lds_dwordx4 v142, s[72:73]
	s_branch .Lhp_e16

.Lhp_e16:
	s_waitcnt vmcnt(8)
	s_barrier
	s_setprio 1
	v_mfma_f32_16x16x32_bf16 v[72:75], v[232:235], v[196:199], v[72:75]
	v_mfma_f32_16x16x32_bf16 v[68:71], v[240:243], v[196:199], v[68:71]
	v_mfma_f32_16x16x32_bf16 v[52:55], v[232:235], v[204:207], v[52:55]
	v_mfma_f32_16x16x32_bf16 v[48:51], v[240:243], v[204:207], v[48:51]
	v_mfma_f32_16x16x32_bf16 v[32:35], v[232:235], v[212:215], v[32:35]
	v_mfma_f32_16x16x32_bf16 v[28:31], v[240:243], v[212:215], v[28:31]
	v_mfma_f32_16x16x32_bf16 v[14:17], v[232:235], v[220:223], v[14:17]
	v_mfma_f32_16x16x32_bf16 v[10:13], v[240:243], v[220:223], v[10:13]
	v_mfma_f32_16x16x32_bf16 v[72:75], v[236:239], v[200:203], v[72:75]
	v_mfma_f32_16x16x32_bf16 v[68:71], v[244:247], v[200:203], v[68:71]
	v_mfma_f32_16x16x32_bf16 v[52:55], v[236:239], v[208:211], v[52:55]
	v_mfma_f32_16x16x32_bf16 v[48:51], v[244:247], v[208:211], v[48:51]
	v_mfma_f32_16x16x32_bf16 v[32:35], v[236:239], v[216:219], v[32:35]
	v_mfma_f32_16x16x32_bf16 v[28:31], v[244:247], v[216:219], v[28:31]
	v_mfma_f32_16x16x32_bf16 v[14:17], v[236:239], v[224:227], v[14:17]
	v_mfma_f32_16x16x32_bf16 v[10:13], v[244:247], v[224:227], v[10:13]
	s_setprio 0
	s_add_u32 s0, s0, 0x100
	s_addc_u32 s1, s1, 0
	v_lshl_add_u64 v[134:135], v[134:135], 0, s[20:21]
	v_lshl_add_u64 v[132:133], v[132:133], 0, s[20:21]
	s_cmp_ge_u32 s6, s86
	s_mov_b32 s2, s6
	s_barrier
	s_cbranch_scc0 .LBB0_894
	s_and_b64 vcc, exec, s[26:27]
	s_cbranch_vccz .LBB0_1126
	v_add_u32_e32 v148, s81, v166
	v_add_u32_e32 v132, s62, v168
	s_mov_b64 s[2:3], -1
	s_mov_b64 s[0:1], 0
	s_cmp_lt_i32 s63, 4
	s_mov_b64 s[76:77], 0
	s_cbranch_scc1 .LBB0_928
	s_cmp_gt_i32 s63, 6
	s_cbranch_scc0 .LBB0_921
	s_cmp_gt_i32 s63, 7
	s_cbranch_scc0 .LBB0_902
	s_cmp_eq_u32 s63, 8
	s_mov_b64 s[76:77], -1
	s_cbranch_scc0 .LBB0_901
	v_ashrrev_i32_e32 v149, 31, v148
	v_lshl_add_u64 v[134:135], v[148:149], 2, s[42:43]
	global_load_dword v198, v[134:135], off
	global_load_dword v200, v[134:135], off offset:64
	global_load_dword v202, v[134:135], off offset:128
	global_load_dword v204, v[134:135], off offset:192
	global_load_dword v206, v[134:135], off offset:512
	global_load_dword v208, v[134:135], off offset:576
	global_load_dword v210, v[134:135], off offset:640
	global_load_dword v212, v[134:135], off offset:704
	s_mov_b32 s6, 0x800000
	v_add_u32_e32 v152, v132, v167
	v_mov_b64_e32 v[150:151], s[44:45]
	s_movk_i32 s7, 0x2c00
	v_ashrrev_i32_e32 v153, 31, v152
	v_mad_i64_i32 v[160:161], s[2:3], v148, s7, v[150:151]
	v_lshlrev_b64 v[152:153], 1, v[152:153]
	v_lshl_add_u64 v[160:161], v[160:161], 0, v[152:153]
	s_mov_b64 s[2:3], 0x2c000
	v_lshl_add_u64 v[214:215], v[160:161], 0, s[2:3]
	v_lshl_add_u64 v[216:217], v[214:215], 0, s[2:3]
	v_lshl_add_u64 v[218:219], v[216:217], 0, s[2:3]
	s_mov_b64 s[2:3], 0x160000
	v_lshl_add_u64 v[220:221], v[160:161], 0, s[2:3]
	v_lshl_add_u64 v[222:223], v[214:215], 0, s[2:3]
	v_lshl_add_u64 v[224:225], v[216:217], 0, s[2:3]
	v_lshl_add_u64 v[226:227], v[218:219], 0, s[2:3]
	s_mov_b64 s[76:77], 0
	s_waitcnt vmcnt(0)
	v_fmamk_f32 v198, v198, 0x3a800000, v172
	v_fmamk_f32 v200, v200, 0x3a800000, v172
	v_fmamk_f32 v202, v202, 0x3a800000, v172
	v_fmamk_f32 v204, v204, 0x3a800000, v172
	v_fmamk_f32 v206, v206, 0x3a800000, v172
	v_fmamk_f32 v208, v208, 0x3a800000, v172
	v_fmamk_f32 v210, v210, 0x3a800000, v172
	v_fmamk_f32 v212, v212, 0x3a800000, v172
	v_rsq_f32_e32 v198, v198
	v_rsq_f32_e32 v200, v200
	v_rsq_f32_e32 v202, v202
	v_rsq_f32_e32 v204, v204
	v_rsq_f32_e32 v206, v206
	v_rsq_f32_e32 v208, v208
	v_rsq_f32_e32 v210, v210
	v_rsq_f32_e32 v212, v212
	s_nop 0
	v_pk_mul_f32 v[128:129], v[128:129], v[198:199] op_sel_hi:[1,0]
	v_pk_mul_f32 v[130:131], v[130:131], v[198:199] op_sel_hi:[1,0]
	v_pk_mul_f32 v[124:125], v[124:125], v[198:199] op_sel_hi:[1,0]
	v_pk_mul_f32 v[126:127], v[126:127], v[198:199] op_sel_hi:[1,0]
	v_cvt_pk_bf16_f32 v128, v128, v129
	v_cvt_pk_bf16_f32 v129, v130, v131
	v_cvt_pk_bf16_f32 v130, v124, v125
	v_cvt_pk_bf16_f32 v131, v126, v127
	global_store_dwordx4 v[160:161], v[128:131], off
	v_pk_mul_f32 v[120:121], v[120:121], v[198:199] op_sel_hi:[1,0]
	v_pk_mul_f32 v[122:123], v[122:123], v[198:199] op_sel_hi:[1,0]
	v_pk_mul_f32 v[116:117], v[116:117], v[198:199] op_sel_hi:[1,0]
	v_pk_mul_f32 v[118:119], v[118:119], v[198:199] op_sel_hi:[1,0]
	v_cvt_pk_bf16_f32 v120, v120, v121
	v_cvt_pk_bf16_f32 v121, v122, v123
	v_cvt_pk_bf16_f32 v122, v116, v117
	v_cvt_pk_bf16_f32 v123, v118, v119
	global_store_dwordx4 v[160:161], v[120:123], off offset:256
	v_pk_mul_f32 v[108:109], v[108:109], v[200:201] op_sel_hi:[1,0]
	v_pk_mul_f32 v[110:111], v[110:111], v[200:201] op_sel_hi:[1,0]
	v_pk_mul_f32 v[100:101], v[100:101], v[200:201] op_sel_hi:[1,0]
	v_pk_mul_f32 v[102:103], v[102:103], v[200:201] op_sel_hi:[1,0]
	v_cvt_pk_bf16_f32 v108, v108, v109
	v_cvt_pk_bf16_f32 v109, v110, v111
	v_cvt_pk_bf16_f32 v110, v100, v101
	v_cvt_pk_bf16_f32 v111, v102, v103
	global_store_dwordx4 v[214:215], v[108:111], off
	v_pk_mul_f32 v[112:113], v[112:113], v[200:201] op_sel_hi:[1,0]
	v_pk_mul_f32 v[114:115], v[114:115], v[200:201] op_sel_hi:[1,0]
	v_pk_mul_f32 v[104:105], v[104:105], v[200:201] op_sel_hi:[1,0]
	v_pk_mul_f32 v[106:107], v[106:107], v[200:201] op_sel_hi:[1,0]
	v_cvt_pk_bf16_f32 v112, v112, v113
	v_cvt_pk_bf16_f32 v113, v114, v115
	v_cvt_pk_bf16_f32 v114, v104, v105
	v_cvt_pk_bf16_f32 v115, v106, v107
	global_store_dwordx4 v[214:215], v[112:115], off offset:256
	v_pk_mul_f32 v[88:89], v[88:89], v[202:203] op_sel_hi:[1,0]
	v_pk_mul_f32 v[90:91], v[90:91], v[202:203] op_sel_hi:[1,0]
	v_pk_mul_f32 v[84:85], v[84:85], v[202:203] op_sel_hi:[1,0]
	v_pk_mul_f32 v[86:87], v[86:87], v[202:203] op_sel_hi:[1,0]
	v_cvt_pk_bf16_f32 v88, v88, v89
	v_cvt_pk_bf16_f32 v89, v90, v91
	v_cvt_pk_bf16_f32 v90, v84, v85
	v_cvt_pk_bf16_f32 v91, v86, v87
	global_store_dwordx4 v[216:217], v[88:91], off
	v_pk_mul_f32 v[96:97], v[96:97], v[202:203] op_sel_hi:[1,0]
	v_pk_mul_f32 v[98:99], v[98:99], v[202:203] op_sel_hi:[1,0]
	v_pk_mul_f32 v[92:93], v[92:93], v[202:203] op_sel_hi:[1,0]
	v_pk_mul_f32 v[94:95], v[94:95], v[202:203] op_sel_hi:[1,0]
	v_cvt_pk_bf16_f32 v96, v96, v97
	v_cvt_pk_bf16_f32 v97, v98, v99
	v_cvt_pk_bf16_f32 v98, v92, v93
	v_cvt_pk_bf16_f32 v99, v94, v95
	global_store_dwordx4 v[216:217], v[96:99], off offset:256
	v_pk_mul_f32 v[56:57], v[56:57], v[204:205] op_sel_hi:[1,0]
	v_pk_mul_f32 v[58:59], v[58:59], v[204:205] op_sel_hi:[1,0]
	v_pk_mul_f32 v[44:45], v[44:45], v[204:205] op_sel_hi:[1,0]
	v_pk_mul_f32 v[46:47], v[46:47], v[204:205] op_sel_hi:[1,0]
	v_cvt_pk_bf16_f32 v56, v56, v57
	v_cvt_pk_bf16_f32 v57, v58, v59
	v_cvt_pk_bf16_f32 v58, v44, v45
	v_cvt_pk_bf16_f32 v59, v46, v47
	global_store_dwordx4 v[218:219], v[56:59], off
	v_pk_mul_f32 v[80:81], v[80:81], v[204:205] op_sel_hi:[1,0]
	v_pk_mul_f32 v[82:83], v[82:83], v[204:205] op_sel_hi:[1,0]
	v_pk_mul_f32 v[76:77], v[76:77], v[204:205] op_sel_hi:[1,0]
	v_pk_mul_f32 v[78:79], v[78:79], v[204:205] op_sel_hi:[1,0]
	v_cvt_pk_bf16_f32 v80, v80, v81
	v_cvt_pk_bf16_f32 v81, v82, v83
	v_cvt_pk_bf16_f32 v82, v76, v77
	v_cvt_pk_bf16_f32 v83, v78, v79
	global_store_dwordx4 v[218:219], v[80:83], off offset:256
	v_pk_mul_f32 v[64:65], v[64:65], v[206:207] op_sel_hi:[1,0]
	v_pk_mul_f32 v[66:67], v[66:67], v[206:207] op_sel_hi:[1,0]
	v_pk_mul_f32 v[60:61], v[60:61], v[206:207] op_sel_hi:[1,0]
	v_pk_mul_f32 v[62:63], v[62:63], v[206:207] op_sel_hi:[1,0]
	v_cvt_pk_bf16_f32 v64, v64, v65
	v_cvt_pk_bf16_f32 v65, v66, v67
	v_cvt_pk_bf16_f32 v66, v60, v61
	v_cvt_pk_bf16_f32 v67, v62, v63
	global_store_dwordx4 v[220:221], v[64:67], off
	v_pk_mul_f32 v[72:73], v[72:73], v[206:207] op_sel_hi:[1,0]
	v_pk_mul_f32 v[74:75], v[74:75], v[206:207] op_sel_hi:[1,0]
	v_pk_mul_f32 v[68:69], v[68:69], v[206:207] op_sel_hi:[1,0]
	v_pk_mul_f32 v[70:71], v[70:71], v[206:207] op_sel_hi:[1,0]
	v_cvt_pk_bf16_f32 v72, v72, v73
	v_cvt_pk_bf16_f32 v73, v74, v75
	v_cvt_pk_bf16_f32 v74, v68, v69
	v_cvt_pk_bf16_f32 v75, v70, v71
	global_store_dwordx4 v[220:221], v[72:75], off offset:256
	v_pk_mul_f32 v[40:41], v[40:41], v[208:209] op_sel_hi:[1,0]
	v_pk_mul_f32 v[42:43], v[42:43], v[208:209] op_sel_hi:[1,0]
	v_pk_mul_f32 v[36:37], v[36:37], v[208:209] op_sel_hi:[1,0]
	v_pk_mul_f32 v[38:39], v[38:39], v[208:209] op_sel_hi:[1,0]
	v_cvt_pk_bf16_f32 v40, v40, v41
	v_cvt_pk_bf16_f32 v41, v42, v43
	v_cvt_pk_bf16_f32 v42, v36, v37
	v_cvt_pk_bf16_f32 v43, v38, v39
	global_store_dwordx4 v[222:223], v[40:43], off
	v_pk_mul_f32 v[52:53], v[52:53], v[208:209] op_sel_hi:[1,0]
	v_pk_mul_f32 v[54:55], v[54:55], v[208:209] op_sel_hi:[1,0]
	v_pk_mul_f32 v[48:49], v[48:49], v[208:209] op_sel_hi:[1,0]
	v_pk_mul_f32 v[50:51], v[50:51], v[208:209] op_sel_hi:[1,0]
	v_cvt_pk_bf16_f32 v52, v52, v53
	v_cvt_pk_bf16_f32 v53, v54, v55
	v_cvt_pk_bf16_f32 v54, v48, v49
	v_cvt_pk_bf16_f32 v55, v50, v51
	global_store_dwordx4 v[222:223], v[52:55], off offset:256
	v_pk_mul_f32 v[22:23], v[22:23], v[210:211] op_sel_hi:[1,0]
	v_pk_mul_f32 v[24:25], v[24:25], v[210:211] op_sel_hi:[1,0]
	v_pk_mul_f32 v[18:19], v[18:19], v[210:211] op_sel_hi:[1,0]
	v_pk_mul_f32 v[20:21], v[20:21], v[210:211] op_sel_hi:[1,0]
	v_cvt_pk_bf16_f32 v22, v22, v23
	v_cvt_pk_bf16_f32 v23, v24, v25
	v_cvt_pk_bf16_f32 v24, v18, v19
	v_cvt_pk_bf16_f32 v25, v20, v21
	global_store_dwordx4 v[224:225], v[22:25], off
	v_pk_mul_f32 v[32:33], v[32:33], v[210:211] op_sel_hi:[1,0]
	v_pk_mul_f32 v[34:35], v[34:35], v[210:211] op_sel_hi:[1,0]
	v_pk_mul_f32 v[28:29], v[28:29], v[210:211] op_sel_hi:[1,0]
	v_pk_mul_f32 v[30:31], v[30:31], v[210:211] op_sel_hi:[1,0]
	v_cvt_pk_bf16_f32 v32, v32, v33
	v_cvt_pk_bf16_f32 v33, v34, v35
	v_cvt_pk_bf16_f32 v34, v28, v29
	v_cvt_pk_bf16_f32 v35, v30, v31
	global_store_dwordx4 v[224:225], v[32:35], off offset:256
	v_pk_mul_f32 v[6:7], v[6:7], v[212:213] op_sel_hi:[1,0]
	v_pk_mul_f32 v[8:9], v[8:9], v[212:213] op_sel_hi:[1,0]
	v_pk_mul_f32 v[2:3], v[2:3], v[212:213] op_sel_hi:[1,0]
	v_pk_mul_f32 v[4:5], v[4:5], v[212:213] op_sel_hi:[1,0]
	v_cvt_pk_bf16_f32 v6, v6, v7
	v_cvt_pk_bf16_f32 v7, v8, v9
	v_cvt_pk_bf16_f32 v8, v2, v3
	v_cvt_pk_bf16_f32 v9, v4, v5
	global_store_dwordx4 v[226:227], v[6:9], off
	v_pk_mul_f32 v[14:15], v[14:15], v[212:213] op_sel_hi:[1,0]
	v_pk_mul_f32 v[16:17], v[16:17], v[212:213] op_sel_hi:[1,0]
	v_pk_mul_f32 v[10:11], v[10:11], v[212:213] op_sel_hi:[1,0]
	v_pk_mul_f32 v[12:13], v[12:13], v[212:213] op_sel_hi:[1,0]
	v_cvt_pk_bf16_f32 v14, v14, v15
	v_cvt_pk_bf16_f32 v15, v16, v17
	v_cvt_pk_bf16_f32 v16, v10, v11
	v_cvt_pk_bf16_f32 v17, v12, v13
	global_store_dwordx4 v[226:227], v[14:17], off offset:256

.LBB0_902:
	s_and_b64 vcc, exec, s[2:3]
	s_cbranch_vccz .LBB0_920
	v_ashrrev_i32_e32 v149, 31, v148
	v_add_u32_e32 v134, v132, v167
	v_ashrrev_i32_e32 v135, 31, v134
	v_lshlrev_b64 v[250:251], 11, v[148:149]
	v_lshl_add_u64 v[250:251], s[46:47], 0, v[250:251]
	v_lshl_add_u64 v[250:251], v[134:135], 1, v[250:251]
	v_lshl_add_u64 v[252:253], v[148:149], 2, s[42:43]
	v_xor_b32_e32 v132, 16, v230
	v_xor_b32_e32 v133, 32, v230
	v_lshlrev_b32_e32 v132, 2, v132
	v_lshlrev_b32_e32 v133, 2, v133
	v_mov_b64_e32 v[248:249], v[250:251]
	s_cmp_eq_u32 s32, 0
	s_cbranch_scc1 .Lrmw_gl_903
	s_mov_b32 s32, 0
	s_mov_b64 s[2:3], 0x58000
	v_lshl_add_u64 v[248:249], v[250:251], 0, s[2:3]
	s_waitcnt vmcnt(0)
	global_load_dwordx4 v[156:159], v[248:249], off
	global_load_dwordx4 v[160:163], v[248:249], off offset:256
	v_lshlrev_b32_e32 v248, 4, v174
	v_add_u32_e32 v249, 0x10000, v248
	ds_read_b128 v[196:199], v249
	ds_read_b128 v[200:203], v249 offset:8192
	ds_read_b128 v[204:207], v248
	ds_read_b128 v[208:211], v248 offset:8192
	ds_read_b128 v[212:215], v249 offset:16384
	ds_read_b128 v[216:219], v249 offset:24576
	ds_read_b128 v[220:223], v248 offset:16384
	ds_read_b128 v[224:227], v248 offset:24576
	ds_read_b128 v[232:235], v249 offset:32768
	ds_read_b128 v[236:239], v249 offset:40960
	ds_read_b128 v[240:243], v248 offset:32768
	ds_read_b128 v[244:247], v248 offset:40960
	ds_read_b128 v[148:151], v249 offset:49152
	ds_read_b128 v[152:155], v249 offset:57344
	s_mov_b64 s[2:3], 0x8000
	s_waitcnt lgkmcnt(0)
	s_branch .Lrmw_go_903
.Lrmw_gl_903:
	global_load_dwordx4 v[196:199], v[248:249], off
	global_load_dwordx4 v[200:203], v[248:249], off offset:256
	s_mov_b64 s[2:3], 0x8000
	v_lshl_add_u64 v[248:249], v[248:249], 0, s[2:3]
	global_load_dwordx4 v[204:207], v[248:249], off
	global_load_dwordx4 v[208:211], v[248:249], off offset:256
	v_lshl_add_u64 v[248:249], v[248:249], 0, s[2:3]
	global_load_dwordx4 v[212:215], v[248:249], off
	global_load_dwordx4 v[216:219], v[248:249], off offset:256
	v_lshl_add_u64 v[248:249], v[248:249], 0, s[2:3]
	global_load_dwordx4 v[220:223], v[248:249], off
	global_load_dwordx4 v[224:227], v[248:249], off offset:256
	s_mov_b64 s[2:3], 0x28000
	v_lshl_add_u64 v[248:249], v[248:249], 0, s[2:3]
	global_load_dwordx4 v[232:235], v[248:249], off
	global_load_dwordx4 v[236:239], v[248:249], off offset:256
	s_mov_b64 s[2:3], 0x8000
	v_lshl_add_u64 v[248:249], v[248:249], 0, s[2:3]
	global_load_dwordx4 v[240:243], v[248:249], off
	global_load_dwordx4 v[244:247], v[248:249], off offset:256
	v_lshl_add_u64 v[248:249], v[248:249], 0, s[2:3]
	global_load_dwordx4 v[148:151], v[248:249], off
	global_load_dwordx4 v[152:155], v[248:249], off offset:256
	v_lshl_add_u64 v[248:249], v[248:249], 0, s[2:3]
	global_load_dwordx4 v[156:159], v[248:249], off
	global_load_dwordx4 v[160:163], v[248:249], off offset:256
.Lrmw_go_903:
	s_waitcnt vmcnt(14)
	v_lshlrev_b32_e32 v134, 16, v196
	v_and_b32_e32 v135, 0xffff0000, v196
	v_pk_add_f32 v[128:129], v[128:129], v[134:135]
	v_lshlrev_b32_e32 v196, 16, v197
	v_and_b32_e32 v197, 0xffff0000, v197
	v_pk_add_f32 v[130:131], v[130:131], v[196:197]
	v_lshlrev_b32_e32 v134, 16, v198
	v_and_b32_e32 v135, 0xffff0000, v198
	v_pk_add_f32 v[124:125], v[124:125], v[134:135]
	v_lshlrev_b32_e32 v198, 16, v199
	v_and_b32_e32 v199, 0xffff0000, v199
	v_pk_add_f32 v[126:127], v[126:127], v[198:199]
	v_lshlrev_b32_e32 v134, 16, v200
	v_and_b32_e32 v135, 0xffff0000, v200
	v_pk_add_f32 v[120:121], v[120:121], v[134:135]
	v_lshlrev_b32_e32 v200, 16, v201
	v_and_b32_e32 v201, 0xffff0000, v201
	v_pk_add_f32 v[122:123], v[122:123], v[200:201]
	v_lshlrev_b32_e32 v134, 16, v202
	v_and_b32_e32 v135, 0xffff0000, v202
	v_pk_add_f32 v[116:117], v[116:117], v[134:135]
	v_lshlrev_b32_e32 v202, 16, v203
	v_and_b32_e32 v203, 0xffff0000, v203
	v_pk_add_f32 v[118:119], v[118:119], v[202:203]
	v_mul_f32_e32 v196, v129, v129
	v_mul_f32_e32 v197, v131, v131
	v_fmac_f32_e32 v196, v128, v128
	v_fmac_f32_e32 v197, v130, v130
	v_mul_f32_e32 v198, v125, v125
	v_mul_f32_e32 v199, v127, v127
	v_add_f32_e32 v196, v196, v197
	v_fmac_f32_e32 v198, v124, v124
	v_fmac_f32_e32 v199, v126, v126
	v_cvt_pk_bf16_f32 v128, v128, v129
	v_add_f32_e32 v198, v198, v199
	v_cvt_pk_bf16_f32 v129, v130, v131
	v_add_f32_e32 v196, v196, v198
	v_cvt_pk_bf16_f32 v130, v124, v125
	v_cvt_pk_bf16_f32 v131, v126, v127
	global_store_dwordx4 v[250:251], v[128:131], off
	v_mul_f32_e32 v200, v121, v121
	v_mul_f32_e32 v201, v123, v123
	v_fmac_f32_e32 v200, v120, v120
	v_fmac_f32_e32 v201, v122, v122
	v_mul_f32_e32 v202, v117, v117
	v_mul_f32_e32 v203, v119, v119
	v_add_f32_e32 v200, v200, v201
	v_fmac_f32_e32 v202, v116, v116
	v_fmac_f32_e32 v203, v118, v118
	v_cvt_pk_bf16_f32 v120, v120, v121
	v_add_f32_e32 v202, v202, v203
	v_cvt_pk_bf16_f32 v121, v122, v123
	v_add_f32_e32 v200, v200, v202
	v_cvt_pk_bf16_f32 v122, v116, v117
	v_cvt_pk_bf16_f32 v123, v118, v119
	global_store_dwordx4 v[250:251], v[120:123], off offset:256
	v_add_f32_e32 v124, v196, v200
	v_lshl_add_u64 v[250:251], v[250:251], 0, s[2:3]
	s_waitcnt vmcnt(14)
	v_lshlrev_b32_e32 v134, 16, v204
	v_and_b32_e32 v135, 0xffff0000, v204
	v_pk_add_f32 v[108:109], v[108:109], v[134:135]
	v_lshlrev_b32_e32 v204, 16, v205
	v_and_b32_e32 v205, 0xffff0000, v205
	v_pk_add_f32 v[110:111], v[110:111], v[204:205]
	v_lshlrev_b32_e32 v134, 16, v206
	v_and_b32_e32 v135, 0xffff0000, v206
	v_pk_add_f32 v[100:101], v[100:101], v[134:135]
	v_lshlrev_b32_e32 v206, 16, v207
	v_and_b32_e32 v207, 0xffff0000, v207
	v_pk_add_f32 v[102:103], v[102:103], v[206:207]
	v_lshlrev_b32_e32 v134, 16, v208
	v_and_b32_e32 v135, 0xffff0000, v208
	v_pk_add_f32 v[112:113], v[112:113], v[134:135]
	v_lshlrev_b32_e32 v208, 16, v209
	v_and_b32_e32 v209, 0xffff0000, v209
	v_pk_add_f32 v[114:115], v[114:115], v[208:209]
	v_lshlrev_b32_e32 v134, 16, v210
	v_and_b32_e32 v135, 0xffff0000, v210
	v_pk_add_f32 v[104:105], v[104:105], v[134:135]
	v_lshlrev_b32_e32 v210, 16, v211
	v_and_b32_e32 v211, 0xffff0000, v211
	v_pk_add_f32 v[106:107], v[106:107], v[210:211]
	v_mul_f32_e32 v204, v109, v109
	v_mul_f32_e32 v205, v111, v111
	v_fmac_f32_e32 v204, v108, v108
	v_fmac_f32_e32 v205, v110, v110
	v_mul_f32_e32 v206, v101, v101
	v_mul_f32_e32 v207, v103, v103
	v_add_f32_e32 v204, v204, v205
	v_fmac_f32_e32 v206, v100, v100
	v_fmac_f32_e32 v207, v102, v102
	v_cvt_pk_bf16_f32 v108, v108, v109
	v_add_f32_e32 v206, v206, v207
	v_cvt_pk_bf16_f32 v109, v110, v111
	v_add_f32_e32 v204, v204, v206
	v_cvt_pk_bf16_f32 v110, v100, v101
	v_cvt_pk_bf16_f32 v111, v102, v103
	global_store_dwordx4 v[250:251], v[108:111], off
	v_mul_f32_e32 v208, v113, v113
	v_mul_f32_e32 v209, v115, v115
	v_fmac_f32_e32 v208, v112, v112
	v_fmac_f32_e32 v209, v114, v114
	v_mul_f32_e32 v210, v105, v105
	v_mul_f32_e32 v211, v107, v107
	v_add_f32_e32 v208, v208, v209
	v_fmac_f32_e32 v210, v104, v104
	v_fmac_f32_e32 v211, v106, v106
	v_cvt_pk_bf16_f32 v112, v112, v113
	v_add_f32_e32 v210, v210, v211
	v_cvt_pk_bf16_f32 v113, v114, v115
	v_add_f32_e32 v208, v208, v210
	v_cvt_pk_bf16_f32 v114, v104, v105
	v_cvt_pk_bf16_f32 v115, v106, v107
	global_store_dwordx4 v[250:251], v[112:115], off offset:256
	v_add_f32_e32 v100, v204, v208
	v_lshl_add_u64 v[250:251], v[250:251], 0, s[2:3]
	s_waitcnt vmcnt(14)
	v_lshlrev_b32_e32 v134, 16, v212
	v_and_b32_e32 v135, 0xffff0000, v212
	v_pk_add_f32 v[88:89], v[88:89], v[134:135]
	v_lshlrev_b32_e32 v212, 16, v213
	v_and_b32_e32 v213, 0xffff0000, v213
	v_pk_add_f32 v[90:91], v[90:91], v[212:213]
	v_lshlrev_b32_e32 v134, 16, v214
	v_and_b32_e32 v135, 0xffff0000, v214
	v_pk_add_f32 v[84:85], v[84:85], v[134:135]
	v_lshlrev_b32_e32 v214, 16, v215
	v_and_b32_e32 v215, 0xffff0000, v215
	v_pk_add_f32 v[86:87], v[86:87], v[214:215]
	v_lshlrev_b32_e32 v134, 16, v216
	v_and_b32_e32 v135, 0xffff0000, v216
	v_pk_add_f32 v[96:97], v[96:97], v[134:135]
	v_lshlrev_b32_e32 v216, 16, v217
	v_and_b32_e32 v217, 0xffff0000, v217
	v_pk_add_f32 v[98:99], v[98:99], v[216:217]
	v_lshlrev_b32_e32 v134, 16, v218
	v_and_b32_e32 v135, 0xffff0000, v218
	v_pk_add_f32 v[92:93], v[92:93], v[134:135]
	v_lshlrev_b32_e32 v218, 16, v219
	v_and_b32_e32 v219, 0xffff0000, v219
	v_pk_add_f32 v[94:95], v[94:95], v[218:219]
	v_mul_f32_e32 v212, v89, v89
	v_mul_f32_e32 v213, v91, v91
	v_fmac_f32_e32 v212, v88, v88
	v_fmac_f32_e32 v213, v90, v90
	v_mul_f32_e32 v214, v85, v85
	v_mul_f32_e32 v215, v87, v87
	v_add_f32_e32 v212, v212, v213
	v_fmac_f32_e32 v214, v84, v84
	v_fmac_f32_e32 v215, v86, v86
	v_cvt_pk_bf16_f32 v88, v88, v89
	v_add_f32_e32 v214, v214, v215
	v_cvt_pk_bf16_f32 v89, v90, v91
	v_add_f32_e32 v212, v212, v214
	v_cvt_pk_bf16_f32 v90, v84, v85
	v_cvt_pk_bf16_f32 v91, v86, v87
	global_store_dwordx4 v[250:251], v[88:91], off
	v_mul_f32_e32 v216, v97, v97
	v_mul_f32_e32 v217, v99, v99
	v_fmac_f32_e32 v216, v96, v96
	v_fmac_f32_e32 v217, v98, v98
	v_mul_f32_e32 v218, v93, v93
	v_mul_f32_e32 v219, v95, v95
	v_add_f32_e32 v216, v216, v217
	v_fmac_f32_e32 v218, v92, v92
	v_fmac_f32_e32 v219, v94, v94
	v_cvt_pk_bf16_f32 v96, v96, v97
	v_add_f32_e32 v218, v218, v219
	v_cvt_pk_bf16_f32 v97, v98, v99
	v_add_f32_e32 v216, v216, v218
	v_cvt_pk_bf16_f32 v98, v92, v93
	v_cvt_pk_bf16_f32 v99, v94, v95
	global_store_dwordx4 v[250:251], v[96:99], off offset:256
	v_add_f32_e32 v84, v212, v216
	v_lshl_add_u64 v[250:251], v[250:251], 0, s[2:3]
	s_waitcnt vmcnt(14)
	v_lshlrev_b32_e32 v134, 16, v220
	v_and_b32_e32 v135, 0xffff0000, v220
	v_pk_add_f32 v[56:57], v[56:57], v[134:135]
	v_lshlrev_b32_e32 v220, 16, v221
	v_and_b32_e32 v221, 0xffff0000, v221
	v_pk_add_f32 v[58:59], v[58:59], v[220:221]
	v_lshlrev_b32_e32 v134, 16, v222
	v_and_b32_e32 v135, 0xffff0000, v222
	v_pk_add_f32 v[44:45], v[44:45], v[134:135]
	v_lshlrev_b32_e32 v222, 16, v223
	v_and_b32_e32 v223, 0xffff0000, v223
	v_pk_add_f32 v[46:47], v[46:47], v[222:223]
	v_lshlrev_b32_e32 v134, 16, v224
	v_and_b32_e32 v135, 0xffff0000, v224
	v_pk_add_f32 v[80:81], v[80:81], v[134:135]
	v_lshlrev_b32_e32 v224, 16, v225
	v_and_b32_e32 v225, 0xffff0000, v225
	v_pk_add_f32 v[82:83], v[82:83], v[224:225]
	v_lshlrev_b32_e32 v134, 16, v226
	v_and_b32_e32 v135, 0xffff0000, v226
	v_pk_add_f32 v[76:77], v[76:77], v[134:135]
	v_lshlrev_b32_e32 v226, 16, v227
	v_and_b32_e32 v227, 0xffff0000, v227
	v_pk_add_f32 v[78:79], v[78:79], v[226:227]
	v_mul_f32_e32 v220, v57, v57
	v_mul_f32_e32 v221, v59, v59
	v_fmac_f32_e32 v220, v56, v56
	v_fmac_f32_e32 v221, v58, v58
	v_mul_f32_e32 v222, v45, v45
	v_mul_f32_e32 v223, v47, v47
	v_add_f32_e32 v220, v220, v221
	v_fmac_f32_e32 v222, v44, v44
	v_fmac_f32_e32 v223, v46, v46
	v_cvt_pk_bf16_f32 v56, v56, v57
	v_add_f32_e32 v222, v222, v223
	v_cvt_pk_bf16_f32 v57, v58, v59
	v_add_f32_e32 v220, v220, v222
	v_cvt_pk_bf16_f32 v58, v44, v45
	v_cvt_pk_bf16_f32 v59, v46, v47
	global_store_dwordx4 v[250:251], v[56:59], off
	v_mul_f32_e32 v224, v81, v81
	v_mul_f32_e32 v225, v83, v83
	v_fmac_f32_e32 v224, v80, v80
	v_fmac_f32_e32 v225, v82, v82
	v_mul_f32_e32 v226, v77, v77
	v_mul_f32_e32 v227, v79, v79
	v_add_f32_e32 v224, v224, v225
	v_fmac_f32_e32 v226, v76, v76
	v_fmac_f32_e32 v227, v78, v78
	v_cvt_pk_bf16_f32 v80, v80, v81
	v_add_f32_e32 v226, v226, v227
	v_cvt_pk_bf16_f32 v81, v82, v83
	v_add_f32_e32 v224, v224, v226
	v_cvt_pk_bf16_f32 v82, v76, v77
	v_cvt_pk_bf16_f32 v83, v78, v79
	global_store_dwordx4 v[250:251], v[80:83], off offset:256
	v_add_f32_e32 v44, v220, v224
	s_mov_b64 s[2:3], 0x28000
	v_lshl_add_u64 v[250:251], v[250:251], 0, s[2:3]
	s_waitcnt vmcnt(14)
	v_lshlrev_b32_e32 v134, 16, v232
	v_and_b32_e32 v135, 0xffff0000, v232
	v_pk_add_f32 v[64:65], v[64:65], v[134:135]
	v_lshlrev_b32_e32 v232, 16, v233
	v_and_b32_e32 v233, 0xffff0000, v233
	v_pk_add_f32 v[66:67], v[66:67], v[232:233]
	v_lshlrev_b32_e32 v134, 16, v234
	v_and_b32_e32 v135, 0xffff0000, v234
	v_pk_add_f32 v[60:61], v[60:61], v[134:135]
	v_lshlrev_b32_e32 v234, 16, v235
	v_and_b32_e32 v235, 0xffff0000, v235
	v_pk_add_f32 v[62:63], v[62:63], v[234:235]
	v_lshlrev_b32_e32 v134, 16, v236
	v_and_b32_e32 v135, 0xffff0000, v236
	v_pk_add_f32 v[72:73], v[72:73], v[134:135]
	v_lshlrev_b32_e32 v236, 16, v237
	v_and_b32_e32 v237, 0xffff0000, v237
	v_pk_add_f32 v[74:75], v[74:75], v[236:237]
	v_lshlrev_b32_e32 v134, 16, v238
	v_and_b32_e32 v135, 0xffff0000, v238
	v_pk_add_f32 v[68:69], v[68:69], v[134:135]
	v_lshlrev_b32_e32 v238, 16, v239
	v_and_b32_e32 v239, 0xffff0000, v239
	v_pk_add_f32 v[70:71], v[70:71], v[238:239]
	v_mul_f32_e32 v232, v65, v65
	v_mul_f32_e32 v233, v67, v67
	v_fmac_f32_e32 v232, v64, v64
	v_fmac_f32_e32 v233, v66, v66
	v_mul_f32_e32 v234, v61, v61
	v_mul_f32_e32 v235, v63, v63
	v_add_f32_e32 v232, v232, v233
	v_fmac_f32_e32 v234, v60, v60
	v_fmac_f32_e32 v235, v62, v62
	v_cvt_pk_bf16_f32 v64, v64, v65
	v_add_f32_e32 v234, v234, v235
	v_cvt_pk_bf16_f32 v65, v66, v67
	v_add_f32_e32 v232, v232, v234
	v_cvt_pk_bf16_f32 v66, v60, v61
	v_cvt_pk_bf16_f32 v67, v62, v63
	global_store_dwordx4 v[250:251], v[64:67], off
	v_mul_f32_e32 v236, v73, v73
	v_mul_f32_e32 v237, v75, v75
	v_fmac_f32_e32 v236, v72, v72
	v_fmac_f32_e32 v237, v74, v74
	v_mul_f32_e32 v238, v69, v69
	v_mul_f32_e32 v239, v71, v71
	v_add_f32_e32 v236, v236, v237
	v_fmac_f32_e32 v238, v68, v68
	v_fmac_f32_e32 v239, v70, v70
	v_cvt_pk_bf16_f32 v72, v72, v73
	v_add_f32_e32 v238, v238, v239
	v_cvt_pk_bf16_f32 v73, v74, v75
	v_add_f32_e32 v236, v236, v238
	v_cvt_pk_bf16_f32 v74, v68, v69
	v_cvt_pk_bf16_f32 v75, v70, v71
	global_store_dwordx4 v[250:251], v[72:75], off offset:256
	v_add_f32_e32 v60, v232, v236
	s_mov_b64 s[2:3], 0x8000
	v_lshl_add_u64 v[250:251], v[250:251], 0, s[2:3]
	s_waitcnt vmcnt(14)
	v_lshlrev_b32_e32 v134, 16, v240
	v_and_b32_e32 v135, 0xffff0000, v240
	v_pk_add_f32 v[40:41], v[40:41], v[134:135]
	v_lshlrev_b32_e32 v240, 16, v241
	v_and_b32_e32 v241, 0xffff0000, v241
	v_pk_add_f32 v[42:43], v[42:43], v[240:241]
	v_lshlrev_b32_e32 v134, 16, v242
	v_and_b32_e32 v135, 0xffff0000, v242
	v_pk_add_f32 v[36:37], v[36:37], v[134:135]
	v_lshlrev_b32_e32 v242, 16, v243
	v_and_b32_e32 v243, 0xffff0000, v243
	v_pk_add_f32 v[38:39], v[38:39], v[242:243]
	v_lshlrev_b32_e32 v134, 16, v244
	v_and_b32_e32 v135, 0xffff0000, v244
	v_pk_add_f32 v[52:53], v[52:53], v[134:135]
	v_lshlrev_b32_e32 v244, 16, v245
	v_and_b32_e32 v245, 0xffff0000, v245
	v_pk_add_f32 v[54:55], v[54:55], v[244:245]
	v_lshlrev_b32_e32 v134, 16, v246
	v_and_b32_e32 v135, 0xffff0000, v246
	v_pk_add_f32 v[48:49], v[48:49], v[134:135]
	v_lshlrev_b32_e32 v246, 16, v247
	v_and_b32_e32 v247, 0xffff0000, v247
	v_pk_add_f32 v[50:51], v[50:51], v[246:247]
	v_mul_f32_e32 v240, v41, v41
	v_mul_f32_e32 v241, v43, v43
	v_fmac_f32_e32 v240, v40, v40
	v_fmac_f32_e32 v241, v42, v42
	v_mul_f32_e32 v242, v37, v37
	v_mul_f32_e32 v243, v39, v39
	v_add_f32_e32 v240, v240, v241
	v_fmac_f32_e32 v242, v36, v36
	v_fmac_f32_e32 v243, v38, v38
	v_cvt_pk_bf16_f32 v40, v40, v41
	v_add_f32_e32 v242, v242, v243
	v_cvt_pk_bf16_f32 v41, v42, v43
	v_add_f32_e32 v240, v240, v242
	v_cvt_pk_bf16_f32 v42, v36, v37
	v_cvt_pk_bf16_f32 v43, v38, v39
	global_store_dwordx4 v[250:251], v[40:43], off
	v_mul_f32_e32 v244, v53, v53
	v_mul_f32_e32 v245, v55, v55
	v_fmac_f32_e32 v244, v52, v52
	v_fmac_f32_e32 v245, v54, v54
	v_mul_f32_e32 v246, v49, v49
	v_mul_f32_e32 v247, v51, v51
	v_add_f32_e32 v244, v244, v245
	v_fmac_f32_e32 v246, v48, v48
	v_fmac_f32_e32 v247, v50, v50
	v_cvt_pk_bf16_f32 v52, v52, v53
	v_add_f32_e32 v246, v246, v247
	v_cvt_pk_bf16_f32 v53, v54, v55
	v_add_f32_e32 v244, v244, v246
	v_cvt_pk_bf16_f32 v54, v48, v49
	v_cvt_pk_bf16_f32 v55, v50, v51
	global_store_dwordx4 v[250:251], v[52:55], off offset:256
	v_add_f32_e32 v36, v240, v244
	v_lshl_add_u64 v[250:251], v[250:251], 0, s[2:3]
	s_waitcnt vmcnt(14)
	v_lshlrev_b32_e32 v134, 16, v148
	v_and_b32_e32 v135, 0xffff0000, v148
	v_pk_add_f32 v[22:23], v[22:23], v[134:135]
	v_lshlrev_b32_e32 v148, 16, v149
	v_and_b32_e32 v149, 0xffff0000, v149
	v_pk_add_f32 v[24:25], v[24:25], v[148:149]
	v_lshlrev_b32_e32 v134, 16, v150
	v_and_b32_e32 v135, 0xffff0000, v150
	v_pk_add_f32 v[18:19], v[18:19], v[134:135]
	v_lshlrev_b32_e32 v150, 16, v151
	v_and_b32_e32 v151, 0xffff0000, v151
	v_pk_add_f32 v[20:21], v[20:21], v[150:151]
	v_lshlrev_b32_e32 v134, 16, v152
	v_and_b32_e32 v135, 0xffff0000, v152
	v_pk_add_f32 v[32:33], v[32:33], v[134:135]
	v_lshlrev_b32_e32 v152, 16, v153
	v_and_b32_e32 v153, 0xffff0000, v153
	v_pk_add_f32 v[34:35], v[34:35], v[152:153]
	v_lshlrev_b32_e32 v134, 16, v154
	v_and_b32_e32 v135, 0xffff0000, v154
	v_pk_add_f32 v[28:29], v[28:29], v[134:135]
	v_lshlrev_b32_e32 v154, 16, v155
	v_and_b32_e32 v155, 0xffff0000, v155
	v_pk_add_f32 v[30:31], v[30:31], v[154:155]
	v_mul_f32_e32 v148, v23, v23
	v_mul_f32_e32 v149, v25, v25
	v_fmac_f32_e32 v148, v22, v22
	v_fmac_f32_e32 v149, v24, v24
	v_mul_f32_e32 v150, v19, v19
	v_mul_f32_e32 v151, v21, v21
	v_add_f32_e32 v148, v148, v149
	v_fmac_f32_e32 v150, v18, v18
	v_fmac_f32_e32 v151, v20, v20
	v_cvt_pk_bf16_f32 v22, v22, v23
	v_add_f32_e32 v150, v150, v151
	v_cvt_pk_bf16_f32 v23, v24, v25
	v_add_f32_e32 v148, v148, v150
	v_cvt_pk_bf16_f32 v24, v18, v19
	v_cvt_pk_bf16_f32 v25, v20, v21
	global_store_dwordx4 v[250:251], v[22:25], off
	v_mul_f32_e32 v152, v33, v33
	v_mul_f32_e32 v153, v35, v35
	v_fmac_f32_e32 v152, v32, v32
	v_fmac_f32_e32 v153, v34, v34
	v_mul_f32_e32 v154, v29, v29
	v_mul_f32_e32 v155, v31, v31
	v_add_f32_e32 v152, v152, v153
	v_fmac_f32_e32 v154, v28, v28
	v_fmac_f32_e32 v155, v30, v30
	v_cvt_pk_bf16_f32 v32, v32, v33
	v_add_f32_e32 v154, v154, v155
	v_cvt_pk_bf16_f32 v33, v34, v35
	v_add_f32_e32 v152, v152, v154
	v_cvt_pk_bf16_f32 v34, v28, v29
	v_cvt_pk_bf16_f32 v35, v30, v31
	global_store_dwordx4 v[250:251], v[32:35], off offset:256
	v_add_f32_e32 v18, v148, v152
	v_lshl_add_u64 v[250:251], v[250:251], 0, s[2:3]
	s_waitcnt vmcnt(14)
	v_lshlrev_b32_e32 v134, 16, v156
	v_and_b32_e32 v135, 0xffff0000, v156
	v_pk_add_f32 v[6:7], v[6:7], v[134:135]
	v_lshlrev_b32_e32 v156, 16, v157
	v_and_b32_e32 v157, 0xffff0000, v157
	v_pk_add_f32 v[8:9], v[8:9], v[156:157]
	v_lshlrev_b32_e32 v134, 16, v158
	v_and_b32_e32 v135, 0xffff0000, v158
	v_pk_add_f32 v[2:3], v[2:3], v[134:135]
	v_lshlrev_b32_e32 v158, 16, v159
	v_and_b32_e32 v159, 0xffff0000, v159
	v_pk_add_f32 v[4:5], v[4:5], v[158:159]
	v_lshlrev_b32_e32 v134, 16, v160
	v_and_b32_e32 v135, 0xffff0000, v160
	v_pk_add_f32 v[14:15], v[14:15], v[134:135]
	v_lshlrev_b32_e32 v160, 16, v161
	v_and_b32_e32 v161, 0xffff0000, v161
	v_pk_add_f32 v[16:17], v[16:17], v[160:161]
	v_lshlrev_b32_e32 v134, 16, v162
	v_and_b32_e32 v135, 0xffff0000, v162
	v_pk_add_f32 v[10:11], v[10:11], v[134:135]
	v_lshlrev_b32_e32 v162, 16, v163
	v_and_b32_e32 v163, 0xffff0000, v163
	v_pk_add_f32 v[12:13], v[12:13], v[162:163]
	v_mul_f32_e32 v156, v7, v7
	v_mul_f32_e32 v157, v9, v9
	v_fmac_f32_e32 v156, v6, v6
	v_fmac_f32_e32 v157, v8, v8
	v_mul_f32_e32 v158, v3, v3
	v_mul_f32_e32 v159, v5, v5
	v_add_f32_e32 v156, v156, v157
	v_fmac_f32_e32 v158, v2, v2
	v_fmac_f32_e32 v159, v4, v4
	v_cvt_pk_bf16_f32 v6, v6, v7
	v_add_f32_e32 v158, v158, v159
	v_cvt_pk_bf16_f32 v7, v8, v9
	v_add_f32_e32 v156, v156, v158
	v_cvt_pk_bf16_f32 v8, v2, v3
	v_cvt_pk_bf16_f32 v9, v4, v5
	global_store_dwordx4 v[250:251], v[6:9], off
	v_mul_f32_e32 v160, v15, v15
	v_mul_f32_e32 v161, v17, v17
	v_fmac_f32_e32 v160, v14, v14
	v_fmac_f32_e32 v161, v16, v16
	v_mul_f32_e32 v162, v11, v11
	v_mul_f32_e32 v163, v13, v13
	v_add_f32_e32 v160, v160, v161
	v_fmac_f32_e32 v162, v10, v10
	v_fmac_f32_e32 v163, v12, v12
	v_cvt_pk_bf16_f32 v14, v14, v15
	v_add_f32_e32 v162, v162, v163
	v_cvt_pk_bf16_f32 v15, v16, v17
	v_add_f32_e32 v160, v160, v162
	v_cvt_pk_bf16_f32 v16, v10, v11
	v_cvt_pk_bf16_f32 v17, v12, v13
	global_store_dwordx4 v[250:251], v[14:17], off offset:256
	v_add_f32_e32 v2, v156, v160
	ds_bpermute_b32 v125, v132, v124
	ds_bpermute_b32 v101, v132, v100
	ds_bpermute_b32 v85, v132, v84
	ds_bpermute_b32 v45, v132, v44
	ds_bpermute_b32 v61, v132, v60
	ds_bpermute_b32 v37, v132, v36
	ds_bpermute_b32 v19, v132, v18
	ds_bpermute_b32 v3, v132, v2
	s_waitcnt lgkmcnt(0)
	v_add_f32_e32 v124, v124, v125
	v_add_f32_e32 v100, v100, v101
	v_add_f32_e32 v84, v84, v85
	v_add_f32_e32 v44, v44, v45
	v_add_f32_e32 v60, v60, v61
	v_add_f32_e32 v36, v36, v37
	v_add_f32_e32 v18, v18, v19
	v_add_f32_e32 v2, v2, v3
	ds_bpermute_b32 v125, v133, v124
	ds_bpermute_b32 v101, v133, v100
	ds_bpermute_b32 v85, v133, v84
	ds_bpermute_b32 v45, v133, v44
	ds_bpermute_b32 v61, v133, v60
	ds_bpermute_b32 v37, v133, v36
	ds_bpermute_b32 v19, v133, v18
	ds_bpermute_b32 v3, v133, v2
	s_and_saveexec_b64 s[2:3], s[4:5]
	s_cbranch_execz .LBB0_919
	s_waitcnt lgkmcnt(0)
	v_add_f32_e32 v124, v124, v125
	v_add_f32_e32 v100, v100, v101
	v_add_f32_e32 v84, v84, v85
	v_add_f32_e32 v44, v44, v45
	v_add_f32_e32 v60, v60, v61
	v_add_f32_e32 v36, v36, v37
	v_add_f32_e32 v18, v18, v19
	v_add_f32_e32 v2, v2, v3
	global_atomic_add_f32 v[252:253], v124, off
	global_atomic_add_f32 v[252:253], v100, off offset:64
	global_atomic_add_f32 v[252:253], v84, off offset:128
	global_atomic_add_f32 v[252:253], v44, off offset:192
	global_atomic_add_f32 v[252:253], v60, off offset:512
	global_atomic_add_f32 v[252:253], v36, off offset:576
	global_atomic_add_f32 v[252:253], v18, off offset:640
	global_atomic_add_f32 v[252:253], v2, off offset:704

.LBB0_1042:
	v_add_u32_e32 v150, v132, v167
	s_and_b64 vcc, exec, s[76:77]
	v_ashrrev_i32_e32 v149, 31, v148
	v_ashrrev_i32_e32 v151, 31, v150
	s_cbranch_vccz .LBB0_1060
	v_lshlrev_b64 v[250:251], 11, v[148:149]
	v_lshl_add_u64 v[250:251], s[46:47], 0, v[250:251]
	v_lshl_add_u64 v[250:251], v[150:151], 1, v[250:251]
	v_lshl_add_u64 v[252:253], v[148:149], 2, s[58:59]
	v_xor_b32_e32 v132, 16, v230
	v_xor_b32_e32 v133, 32, v230
	v_lshlrev_b32_e32 v132, 2, v132
	v_lshlrev_b32_e32 v133, 2, v133
	v_mov_b64_e32 v[248:249], v[250:251]
	s_waitcnt lgkmcnt(0)
	s_cmp_eq_u32 s32, 0
	s_cbranch_scc1 .Lrmw_gl_1043
	s_mov_b32 s32, 0
	s_mov_b64 s[0:1], 0x58000
	v_lshl_add_u64 v[248:249], v[250:251], 0, s[0:1]
	s_waitcnt vmcnt(0)
	global_load_dwordx4 v[156:159], v[248:249], off
	global_load_dwordx4 v[160:163], v[248:249], off offset:256
	v_lshlrev_b32_e32 v248, 4, v174
	v_add_u32_e32 v249, 0x10000, v248
	ds_read_b128 v[196:199], v249
	ds_read_b128 v[200:203], v249 offset:8192
	ds_read_b128 v[204:207], v248
	ds_read_b128 v[208:211], v248 offset:8192
	ds_read_b128 v[212:215], v249 offset:16384
	ds_read_b128 v[216:219], v249 offset:24576
	ds_read_b128 v[220:223], v248 offset:16384
	ds_read_b128 v[224:227], v248 offset:24576
	ds_read_b128 v[232:235], v249 offset:32768
	ds_read_b128 v[236:239], v249 offset:40960
	ds_read_b128 v[240:243], v248 offset:32768
	ds_read_b128 v[244:247], v248 offset:40960
	ds_read_b128 v[148:151], v249 offset:49152
	ds_read_b128 v[152:155], v249 offset:57344
	s_mov_b64 s[0:1], 0x8000
	s_waitcnt lgkmcnt(0)
	s_branch .Lrmw_go_1043
.Lrmw_gl_1043:
	global_load_dwordx4 v[196:199], v[248:249], off
	global_load_dwordx4 v[200:203], v[248:249], off offset:256
	s_mov_b64 s[0:1], 0x8000
	v_lshl_add_u64 v[248:249], v[248:249], 0, s[0:1]
	global_load_dwordx4 v[204:207], v[248:249], off
	global_load_dwordx4 v[208:211], v[248:249], off offset:256
	v_lshl_add_u64 v[248:249], v[248:249], 0, s[0:1]
	global_load_dwordx4 v[212:215], v[248:249], off
	global_load_dwordx4 v[216:219], v[248:249], off offset:256
	v_lshl_add_u64 v[248:249], v[248:249], 0, s[0:1]
	global_load_dwordx4 v[220:223], v[248:249], off
	global_load_dwordx4 v[224:227], v[248:249], off offset:256
	s_mov_b64 s[0:1], 0x28000
	v_lshl_add_u64 v[248:249], v[248:249], 0, s[0:1]
	global_load_dwordx4 v[232:235], v[248:249], off
	global_load_dwordx4 v[236:239], v[248:249], off offset:256
	s_mov_b64 s[0:1], 0x8000
	v_lshl_add_u64 v[248:249], v[248:249], 0, s[0:1]
	global_load_dwordx4 v[240:243], v[248:249], off
	global_load_dwordx4 v[244:247], v[248:249], off offset:256
	v_lshl_add_u64 v[248:249], v[248:249], 0, s[0:1]
	global_load_dwordx4 v[148:151], v[248:249], off
	global_load_dwordx4 v[152:155], v[248:249], off offset:256
	v_lshl_add_u64 v[248:249], v[248:249], 0, s[0:1]
	global_load_dwordx4 v[156:159], v[248:249], off
	global_load_dwordx4 v[160:163], v[248:249], off offset:256
.Lrmw_go_1043:
	s_waitcnt vmcnt(14)
	v_lshlrev_b32_e32 v134, 16, v196
	v_and_b32_e32 v135, 0xffff0000, v196
	v_pk_add_f32 v[128:129], v[128:129], v[134:135]
	v_lshlrev_b32_e32 v196, 16, v197
	v_and_b32_e32 v197, 0xffff0000, v197
	v_pk_add_f32 v[130:131], v[130:131], v[196:197]
	v_lshlrev_b32_e32 v134, 16, v198
	v_and_b32_e32 v135, 0xffff0000, v198
	v_pk_add_f32 v[124:125], v[124:125], v[134:135]
	v_lshlrev_b32_e32 v198, 16, v199
	v_and_b32_e32 v199, 0xffff0000, v199
	v_pk_add_f32 v[126:127], v[126:127], v[198:199]
	v_lshlrev_b32_e32 v134, 16, v200
	v_and_b32_e32 v135, 0xffff0000, v200
	v_pk_add_f32 v[120:121], v[120:121], v[134:135]
	v_lshlrev_b32_e32 v200, 16, v201
	v_and_b32_e32 v201, 0xffff0000, v201
	v_pk_add_f32 v[122:123], v[122:123], v[200:201]
	v_lshlrev_b32_e32 v134, 16, v202
	v_and_b32_e32 v135, 0xffff0000, v202
	v_pk_add_f32 v[116:117], v[116:117], v[134:135]
	v_lshlrev_b32_e32 v202, 16, v203
	v_and_b32_e32 v203, 0xffff0000, v203
	v_pk_add_f32 v[118:119], v[118:119], v[202:203]
	v_mul_f32_e32 v196, v129, v129
	v_mul_f32_e32 v197, v131, v131
	v_fmac_f32_e32 v196, v128, v128
	v_fmac_f32_e32 v197, v130, v130
	v_mul_f32_e32 v198, v125, v125
	v_mul_f32_e32 v199, v127, v127
	v_add_f32_e32 v196, v196, v197
	v_fmac_f32_e32 v198, v124, v124
	v_fmac_f32_e32 v199, v126, v126
	v_cvt_pk_bf16_f32 v128, v128, v129
	v_add_f32_e32 v198, v198, v199
	v_cvt_pk_bf16_f32 v129, v130, v131
	v_add_f32_e32 v196, v196, v198
	v_cvt_pk_bf16_f32 v130, v124, v125
	v_cvt_pk_bf16_f32 v131, v126, v127
	global_store_dwordx4 v[250:251], v[128:131], off
	v_mul_f32_e32 v200, v121, v121
	v_mul_f32_e32 v201, v123, v123
	v_fmac_f32_e32 v200, v120, v120
	v_fmac_f32_e32 v201, v122, v122
	v_mul_f32_e32 v202, v117, v117
	v_mul_f32_e32 v203, v119, v119
	v_add_f32_e32 v200, v200, v201
	v_fmac_f32_e32 v202, v116, v116
	v_fmac_f32_e32 v203, v118, v118
	v_cvt_pk_bf16_f32 v120, v120, v121
	v_add_f32_e32 v202, v202, v203
	v_cvt_pk_bf16_f32 v121, v122, v123
	v_add_f32_e32 v200, v200, v202
	v_cvt_pk_bf16_f32 v122, v116, v117
	v_cvt_pk_bf16_f32 v123, v118, v119
	global_store_dwordx4 v[250:251], v[120:123], off offset:256
	v_add_f32_e32 v124, v196, v200
	v_lshl_add_u64 v[250:251], v[250:251], 0, s[0:1]
	s_waitcnt vmcnt(14)
	v_lshlrev_b32_e32 v134, 16, v204
	v_and_b32_e32 v135, 0xffff0000, v204
	v_pk_add_f32 v[108:109], v[108:109], v[134:135]
	v_lshlrev_b32_e32 v204, 16, v205
	v_and_b32_e32 v205, 0xffff0000, v205
	v_pk_add_f32 v[110:111], v[110:111], v[204:205]
	v_lshlrev_b32_e32 v134, 16, v206
	v_and_b32_e32 v135, 0xffff0000, v206
	v_pk_add_f32 v[100:101], v[100:101], v[134:135]
	v_lshlrev_b32_e32 v206, 16, v207
	v_and_b32_e32 v207, 0xffff0000, v207
	v_pk_add_f32 v[102:103], v[102:103], v[206:207]
	v_lshlrev_b32_e32 v134, 16, v208
	v_and_b32_e32 v135, 0xffff0000, v208
	v_pk_add_f32 v[112:113], v[112:113], v[134:135]
	v_lshlrev_b32_e32 v208, 16, v209
	v_and_b32_e32 v209, 0xffff0000, v209
	v_pk_add_f32 v[114:115], v[114:115], v[208:209]
	v_lshlrev_b32_e32 v134, 16, v210
	v_and_b32_e32 v135, 0xffff0000, v210
	v_pk_add_f32 v[104:105], v[104:105], v[134:135]
	v_lshlrev_b32_e32 v210, 16, v211
	v_and_b32_e32 v211, 0xffff0000, v211
	v_pk_add_f32 v[106:107], v[106:107], v[210:211]
	v_mul_f32_e32 v204, v109, v109
	v_mul_f32_e32 v205, v111, v111
	v_fmac_f32_e32 v204, v108, v108
	v_fmac_f32_e32 v205, v110, v110
	v_mul_f32_e32 v206, v101, v101
	v_mul_f32_e32 v207, v103, v103
	v_add_f32_e32 v204, v204, v205
	v_fmac_f32_e32 v206, v100, v100
	v_fmac_f32_e32 v207, v102, v102
	v_cvt_pk_bf16_f32 v108, v108, v109
	v_add_f32_e32 v206, v206, v207
	v_cvt_pk_bf16_f32 v109, v110, v111
	v_add_f32_e32 v204, v204, v206
	v_cvt_pk_bf16_f32 v110, v100, v101
	v_cvt_pk_bf16_f32 v111, v102, v103
	global_store_dwordx4 v[250:251], v[108:111], off
	v_mul_f32_e32 v208, v113, v113
	v_mul_f32_e32 v209, v115, v115
	v_fmac_f32_e32 v208, v112, v112
	v_fmac_f32_e32 v209, v114, v114
	v_mul_f32_e32 v210, v105, v105
	v_mul_f32_e32 v211, v107, v107
	v_add_f32_e32 v208, v208, v209
	v_fmac_f32_e32 v210, v104, v104
	v_fmac_f32_e32 v211, v106, v106
	v_cvt_pk_bf16_f32 v112, v112, v113
	v_add_f32_e32 v210, v210, v211
	v_cvt_pk_bf16_f32 v113, v114, v115
	v_add_f32_e32 v208, v208, v210
	v_cvt_pk_bf16_f32 v114, v104, v105
	v_cvt_pk_bf16_f32 v115, v106, v107
	global_store_dwordx4 v[250:251], v[112:115], off offset:256
	v_add_f32_e32 v100, v204, v208
	v_lshl_add_u64 v[250:251], v[250:251], 0, s[0:1]
	s_waitcnt vmcnt(14)
	v_lshlrev_b32_e32 v134, 16, v212
	v_and_b32_e32 v135, 0xffff0000, v212
	v_pk_add_f32 v[88:89], v[88:89], v[134:135]
	v_lshlrev_b32_e32 v212, 16, v213
	v_and_b32_e32 v213, 0xffff0000, v213
	v_pk_add_f32 v[90:91], v[90:91], v[212:213]
	v_lshlrev_b32_e32 v134, 16, v214
	v_and_b32_e32 v135, 0xffff0000, v214
	v_pk_add_f32 v[84:85], v[84:85], v[134:135]
	v_lshlrev_b32_e32 v214, 16, v215
	v_and_b32_e32 v215, 0xffff0000, v215
	v_pk_add_f32 v[86:87], v[86:87], v[214:215]
	v_lshlrev_b32_e32 v134, 16, v216
	v_and_b32_e32 v135, 0xffff0000, v216
	v_pk_add_f32 v[96:97], v[96:97], v[134:135]
	v_lshlrev_b32_e32 v216, 16, v217
	v_and_b32_e32 v217, 0xffff0000, v217
	v_pk_add_f32 v[98:99], v[98:99], v[216:217]
	v_lshlrev_b32_e32 v134, 16, v218
	v_and_b32_e32 v135, 0xffff0000, v218
	v_pk_add_f32 v[92:93], v[92:93], v[134:135]
	v_lshlrev_b32_e32 v218, 16, v219
	v_and_b32_e32 v219, 0xffff0000, v219
	v_pk_add_f32 v[94:95], v[94:95], v[218:219]
	v_mul_f32_e32 v212, v89, v89
	v_mul_f32_e32 v213, v91, v91
	v_fmac_f32_e32 v212, v88, v88
	v_fmac_f32_e32 v213, v90, v90
	v_mul_f32_e32 v214, v85, v85
	v_mul_f32_e32 v215, v87, v87
	v_add_f32_e32 v212, v212, v213
	v_fmac_f32_e32 v214, v84, v84
	v_fmac_f32_e32 v215, v86, v86
	v_cvt_pk_bf16_f32 v88, v88, v89
	v_add_f32_e32 v214, v214, v215
	v_cvt_pk_bf16_f32 v89, v90, v91
	v_add_f32_e32 v212, v212, v214
	v_cvt_pk_bf16_f32 v90, v84, v85
	v_cvt_pk_bf16_f32 v91, v86, v87
	global_store_dwordx4 v[250:251], v[88:91], off
	v_mul_f32_e32 v216, v97, v97
	v_mul_f32_e32 v217, v99, v99
	v_fmac_f32_e32 v216, v96, v96
	v_fmac_f32_e32 v217, v98, v98
	v_mul_f32_e32 v218, v93, v93
	v_mul_f32_e32 v219, v95, v95
	v_add_f32_e32 v216, v216, v217
	v_fmac_f32_e32 v218, v92, v92
	v_fmac_f32_e32 v219, v94, v94
	v_cvt_pk_bf16_f32 v96, v96, v97
	v_add_f32_e32 v218, v218, v219
	v_cvt_pk_bf16_f32 v97, v98, v99
	v_add_f32_e32 v216, v216, v218
	v_cvt_pk_bf16_f32 v98, v92, v93
	v_cvt_pk_bf16_f32 v99, v94, v95
	global_store_dwordx4 v[250:251], v[96:99], off offset:256
	v_add_f32_e32 v84, v212, v216
	v_lshl_add_u64 v[250:251], v[250:251], 0, s[0:1]
	s_waitcnt vmcnt(14)
	v_lshlrev_b32_e32 v134, 16, v220
	v_and_b32_e32 v135, 0xffff0000, v220
	v_pk_add_f32 v[56:57], v[56:57], v[134:135]
	v_lshlrev_b32_e32 v220, 16, v221
	v_and_b32_e32 v221, 0xffff0000, v221
	v_pk_add_f32 v[58:59], v[58:59], v[220:221]
	v_lshlrev_b32_e32 v134, 16, v222
	v_and_b32_e32 v135, 0xffff0000, v222
	v_pk_add_f32 v[44:45], v[44:45], v[134:135]
	v_lshlrev_b32_e32 v222, 16, v223
	v_and_b32_e32 v223, 0xffff0000, v223
	v_pk_add_f32 v[46:47], v[46:47], v[222:223]
	v_lshlrev_b32_e32 v134, 16, v224
	v_and_b32_e32 v135, 0xffff0000, v224
	v_pk_add_f32 v[80:81], v[80:81], v[134:135]
	v_lshlrev_b32_e32 v224, 16, v225
	v_and_b32_e32 v225, 0xffff0000, v225
	v_pk_add_f32 v[82:83], v[82:83], v[224:225]
	v_lshlrev_b32_e32 v134, 16, v226
	v_and_b32_e32 v135, 0xffff0000, v226
	v_pk_add_f32 v[76:77], v[76:77], v[134:135]
	v_lshlrev_b32_e32 v226, 16, v227
	v_and_b32_e32 v227, 0xffff0000, v227
	v_pk_add_f32 v[78:79], v[78:79], v[226:227]
	v_mul_f32_e32 v220, v57, v57
	v_mul_f32_e32 v221, v59, v59
	v_fmac_f32_e32 v220, v56, v56
	v_fmac_f32_e32 v221, v58, v58
	v_mul_f32_e32 v222, v45, v45
	v_mul_f32_e32 v223, v47, v47
	v_add_f32_e32 v220, v220, v221
	v_fmac_f32_e32 v222, v44, v44
	v_fmac_f32_e32 v223, v46, v46
	v_cvt_pk_bf16_f32 v56, v56, v57
	v_add_f32_e32 v222, v222, v223
	v_cvt_pk_bf16_f32 v57, v58, v59
	v_add_f32_e32 v220, v220, v222
	v_cvt_pk_bf16_f32 v58, v44, v45
	v_cvt_pk_bf16_f32 v59, v46, v47
	global_store_dwordx4 v[250:251], v[56:59], off
	v_mul_f32_e32 v224, v81, v81
	v_mul_f32_e32 v225, v83, v83
	v_fmac_f32_e32 v224, v80, v80
	v_fmac_f32_e32 v225, v82, v82
	v_mul_f32_e32 v226, v77, v77
	v_mul_f32_e32 v227, v79, v79
	v_add_f32_e32 v224, v224, v225
	v_fmac_f32_e32 v226, v76, v76
	v_fmac_f32_e32 v227, v78, v78
	v_cvt_pk_bf16_f32 v80, v80, v81
	v_add_f32_e32 v226, v226, v227
	v_cvt_pk_bf16_f32 v81, v82, v83
	v_add_f32_e32 v224, v224, v226
	v_cvt_pk_bf16_f32 v82, v76, v77
	v_cvt_pk_bf16_f32 v83, v78, v79
	global_store_dwordx4 v[250:251], v[80:83], off offset:256
	v_add_f32_e32 v44, v220, v224
	s_mov_b64 s[0:1], 0x28000
	v_lshl_add_u64 v[250:251], v[250:251], 0, s[0:1]
	s_waitcnt vmcnt(14)
	v_lshlrev_b32_e32 v134, 16, v232
	v_and_b32_e32 v135, 0xffff0000, v232
	v_pk_add_f32 v[64:65], v[64:65], v[134:135]
	v_lshlrev_b32_e32 v232, 16, v233
	v_and_b32_e32 v233, 0xffff0000, v233
	v_pk_add_f32 v[66:67], v[66:67], v[232:233]
	v_lshlrev_b32_e32 v134, 16, v234
	v_and_b32_e32 v135, 0xffff0000, v234
	v_pk_add_f32 v[60:61], v[60:61], v[134:135]
	v_lshlrev_b32_e32 v234, 16, v235
	v_and_b32_e32 v235, 0xffff0000, v235
	v_pk_add_f32 v[62:63], v[62:63], v[234:235]
	v_lshlrev_b32_e32 v134, 16, v236
	v_and_b32_e32 v135, 0xffff0000, v236
	v_pk_add_f32 v[72:73], v[72:73], v[134:135]
	v_lshlrev_b32_e32 v236, 16, v237
	v_and_b32_e32 v237, 0xffff0000, v237
	v_pk_add_f32 v[74:75], v[74:75], v[236:237]
	v_lshlrev_b32_e32 v134, 16, v238
	v_and_b32_e32 v135, 0xffff0000, v238
	v_pk_add_f32 v[68:69], v[68:69], v[134:135]
	v_lshlrev_b32_e32 v238, 16, v239
	v_and_b32_e32 v239, 0xffff0000, v239
	v_pk_add_f32 v[70:71], v[70:71], v[238:239]
	v_mul_f32_e32 v232, v65, v65
	v_mul_f32_e32 v233, v67, v67
	v_fmac_f32_e32 v232, v64, v64
	v_fmac_f32_e32 v233, v66, v66
	v_mul_f32_e32 v234, v61, v61
	v_mul_f32_e32 v235, v63, v63
	v_add_f32_e32 v232, v232, v233
	v_fmac_f32_e32 v234, v60, v60
	v_fmac_f32_e32 v235, v62, v62
	v_cvt_pk_bf16_f32 v64, v64, v65
	v_add_f32_e32 v234, v234, v235
	v_cvt_pk_bf16_f32 v65, v66, v67
	v_add_f32_e32 v232, v232, v234
	v_cvt_pk_bf16_f32 v66, v60, v61
	v_cvt_pk_bf16_f32 v67, v62, v63
	global_store_dwordx4 v[250:251], v[64:67], off
	v_mul_f32_e32 v236, v73, v73
	v_mul_f32_e32 v237, v75, v75
	v_fmac_f32_e32 v236, v72, v72
	v_fmac_f32_e32 v237, v74, v74
	v_mul_f32_e32 v238, v69, v69
	v_mul_f32_e32 v239, v71, v71
	v_add_f32_e32 v236, v236, v237
	v_fmac_f32_e32 v238, v68, v68
	v_fmac_f32_e32 v239, v70, v70
	v_cvt_pk_bf16_f32 v72, v72, v73
	v_add_f32_e32 v238, v238, v239
	v_cvt_pk_bf16_f32 v73, v74, v75
	v_add_f32_e32 v236, v236, v238
	v_cvt_pk_bf16_f32 v74, v68, v69
	v_cvt_pk_bf16_f32 v75, v70, v71
	global_store_dwordx4 v[250:251], v[72:75], off offset:256
	v_add_f32_e32 v60, v232, v236
	s_mov_b64 s[0:1], 0x8000
	v_lshl_add_u64 v[250:251], v[250:251], 0, s[0:1]
	s_waitcnt vmcnt(14)
	v_lshlrev_b32_e32 v134, 16, v240
	v_and_b32_e32 v135, 0xffff0000, v240
	v_pk_add_f32 v[40:41], v[40:41], v[134:135]
	v_lshlrev_b32_e32 v240, 16, v241
	v_and_b32_e32 v241, 0xffff0000, v241
	v_pk_add_f32 v[42:43], v[42:43], v[240:241]
	v_lshlrev_b32_e32 v134, 16, v242
	v_and_b32_e32 v135, 0xffff0000, v242
	v_pk_add_f32 v[36:37], v[36:37], v[134:135]
	v_lshlrev_b32_e32 v242, 16, v243
	v_and_b32_e32 v243, 0xffff0000, v243
	v_pk_add_f32 v[38:39], v[38:39], v[242:243]
	v_lshlrev_b32_e32 v134, 16, v244
	v_and_b32_e32 v135, 0xffff0000, v244
	v_pk_add_f32 v[52:53], v[52:53], v[134:135]
	v_lshlrev_b32_e32 v244, 16, v245
	v_and_b32_e32 v245, 0xffff0000, v245
	v_pk_add_f32 v[54:55], v[54:55], v[244:245]
	v_lshlrev_b32_e32 v134, 16, v246
	v_and_b32_e32 v135, 0xffff0000, v246
	v_pk_add_f32 v[48:49], v[48:49], v[134:135]
	v_lshlrev_b32_e32 v246, 16, v247
	v_and_b32_e32 v247, 0xffff0000, v247
	v_pk_add_f32 v[50:51], v[50:51], v[246:247]
	v_mul_f32_e32 v240, v41, v41
	v_mul_f32_e32 v241, v43, v43
	v_fmac_f32_e32 v240, v40, v40
	v_fmac_f32_e32 v241, v42, v42
	v_mul_f32_e32 v242, v37, v37
	v_mul_f32_e32 v243, v39, v39
	v_add_f32_e32 v240, v240, v241
	v_fmac_f32_e32 v242, v36, v36
	v_fmac_f32_e32 v243, v38, v38
	v_cvt_pk_bf16_f32 v40, v40, v41
	v_add_f32_e32 v242, v242, v243
	v_cvt_pk_bf16_f32 v41, v42, v43
	v_add_f32_e32 v240, v240, v242
	v_cvt_pk_bf16_f32 v42, v36, v37
	v_cvt_pk_bf16_f32 v43, v38, v39
	global_store_dwordx4 v[250:251], v[40:43], off
	v_mul_f32_e32 v244, v53, v53
	v_mul_f32_e32 v245, v55, v55
	v_fmac_f32_e32 v244, v52, v52
	v_fmac_f32_e32 v245, v54, v54
	v_mul_f32_e32 v246, v49, v49
	v_mul_f32_e32 v247, v51, v51
	v_add_f32_e32 v244, v244, v245
	v_fmac_f32_e32 v246, v48, v48
	v_fmac_f32_e32 v247, v50, v50
	v_cvt_pk_bf16_f32 v52, v52, v53
	v_add_f32_e32 v246, v246, v247
	v_cvt_pk_bf16_f32 v53, v54, v55
	v_add_f32_e32 v244, v244, v246
	v_cvt_pk_bf16_f32 v54, v48, v49
	v_cvt_pk_bf16_f32 v55, v50, v51
	global_store_dwordx4 v[250:251], v[52:55], off offset:256
	v_add_f32_e32 v36, v240, v244
	v_lshl_add_u64 v[250:251], v[250:251], 0, s[0:1]
	s_waitcnt vmcnt(14)
	v_lshlrev_b32_e32 v134, 16, v148
	v_and_b32_e32 v135, 0xffff0000, v148
	v_pk_add_f32 v[22:23], v[22:23], v[134:135]
	v_lshlrev_b32_e32 v148, 16, v149
	v_and_b32_e32 v149, 0xffff0000, v149
	v_pk_add_f32 v[24:25], v[24:25], v[148:149]
	v_lshlrev_b32_e32 v134, 16, v150
	v_and_b32_e32 v135, 0xffff0000, v150
	v_pk_add_f32 v[18:19], v[18:19], v[134:135]
	v_lshlrev_b32_e32 v150, 16, v151
	v_and_b32_e32 v151, 0xffff0000, v151
	v_pk_add_f32 v[20:21], v[20:21], v[150:151]
	v_lshlrev_b32_e32 v134, 16, v152
	v_and_b32_e32 v135, 0xffff0000, v152
	v_pk_add_f32 v[32:33], v[32:33], v[134:135]
	v_lshlrev_b32_e32 v152, 16, v153
	v_and_b32_e32 v153, 0xffff0000, v153
	v_pk_add_f32 v[34:35], v[34:35], v[152:153]
	v_lshlrev_b32_e32 v134, 16, v154
	v_and_b32_e32 v135, 0xffff0000, v154
	v_pk_add_f32 v[28:29], v[28:29], v[134:135]
	v_lshlrev_b32_e32 v154, 16, v155
	v_and_b32_e32 v155, 0xffff0000, v155
	v_pk_add_f32 v[30:31], v[30:31], v[154:155]
	v_mul_f32_e32 v148, v23, v23
	v_mul_f32_e32 v149, v25, v25
	v_fmac_f32_e32 v148, v22, v22
	v_fmac_f32_e32 v149, v24, v24
	v_mul_f32_e32 v150, v19, v19
	v_mul_f32_e32 v151, v21, v21
	v_add_f32_e32 v148, v148, v149
	v_fmac_f32_e32 v150, v18, v18
	v_fmac_f32_e32 v151, v20, v20
	v_cvt_pk_bf16_f32 v22, v22, v23
	v_add_f32_e32 v150, v150, v151
	v_cvt_pk_bf16_f32 v23, v24, v25
	v_add_f32_e32 v148, v148, v150
	v_cvt_pk_bf16_f32 v24, v18, v19
	v_cvt_pk_bf16_f32 v25, v20, v21
	global_store_dwordx4 v[250:251], v[22:25], off
	v_mul_f32_e32 v152, v33, v33
	v_mul_f32_e32 v153, v35, v35
	v_fmac_f32_e32 v152, v32, v32
	v_fmac_f32_e32 v153, v34, v34
	v_mul_f32_e32 v154, v29, v29
	v_mul_f32_e32 v155, v31, v31
	v_add_f32_e32 v152, v152, v153
	v_fmac_f32_e32 v154, v28, v28
	v_fmac_f32_e32 v155, v30, v30
	v_cvt_pk_bf16_f32 v32, v32, v33
	v_add_f32_e32 v154, v154, v155
	v_cvt_pk_bf16_f32 v33, v34, v35
	v_add_f32_e32 v152, v152, v154
	v_cvt_pk_bf16_f32 v34, v28, v29
	v_cvt_pk_bf16_f32 v35, v30, v31
	global_store_dwordx4 v[250:251], v[32:35], off offset:256
	v_add_f32_e32 v18, v148, v152
	v_lshl_add_u64 v[250:251], v[250:251], 0, s[0:1]
	s_waitcnt vmcnt(14)
	v_lshlrev_b32_e32 v134, 16, v156
	v_and_b32_e32 v135, 0xffff0000, v156
	v_pk_add_f32 v[6:7], v[6:7], v[134:135]
	v_lshlrev_b32_e32 v156, 16, v157
	v_and_b32_e32 v157, 0xffff0000, v157
	v_pk_add_f32 v[8:9], v[8:9], v[156:157]
	v_lshlrev_b32_e32 v134, 16, v158
	v_and_b32_e32 v135, 0xffff0000, v158
	v_pk_add_f32 v[2:3], v[2:3], v[134:135]
	v_lshlrev_b32_e32 v158, 16, v159
	v_and_b32_e32 v159, 0xffff0000, v159
	v_pk_add_f32 v[4:5], v[4:5], v[158:159]
	v_lshlrev_b32_e32 v134, 16, v160
	v_and_b32_e32 v135, 0xffff0000, v160
	v_pk_add_f32 v[14:15], v[14:15], v[134:135]
	v_lshlrev_b32_e32 v160, 16, v161
	v_and_b32_e32 v161, 0xffff0000, v161
	v_pk_add_f32 v[16:17], v[16:17], v[160:161]
	v_lshlrev_b32_e32 v134, 16, v162
	v_and_b32_e32 v135, 0xffff0000, v162
	v_pk_add_f32 v[10:11], v[10:11], v[134:135]
	v_lshlrev_b32_e32 v162, 16, v163
	v_and_b32_e32 v163, 0xffff0000, v163
	v_pk_add_f32 v[12:13], v[12:13], v[162:163]
	v_mul_f32_e32 v156, v7, v7
	v_mul_f32_e32 v157, v9, v9
	v_fmac_f32_e32 v156, v6, v6
	v_fmac_f32_e32 v157, v8, v8
	v_mul_f32_e32 v158, v3, v3
	v_mul_f32_e32 v159, v5, v5
	v_add_f32_e32 v156, v156, v157
	v_fmac_f32_e32 v158, v2, v2
	v_fmac_f32_e32 v159, v4, v4
	v_cvt_pk_bf16_f32 v6, v6, v7
	v_add_f32_e32 v158, v158, v159
	v_cvt_pk_bf16_f32 v7, v8, v9
	v_add_f32_e32 v156, v156, v158
	v_cvt_pk_bf16_f32 v8, v2, v3
	v_cvt_pk_bf16_f32 v9, v4, v5
	global_store_dwordx4 v[250:251], v[6:9], off
	v_mul_f32_e32 v160, v15, v15
	v_mul_f32_e32 v161, v17, v17
	v_fmac_f32_e32 v160, v14, v14
	v_fmac_f32_e32 v161, v16, v16
	v_mul_f32_e32 v162, v11, v11
	v_mul_f32_e32 v163, v13, v13
	v_add_f32_e32 v160, v160, v161
	v_fmac_f32_e32 v162, v10, v10
	v_fmac_f32_e32 v163, v12, v12
	v_cvt_pk_bf16_f32 v14, v14, v15
	v_add_f32_e32 v162, v162, v163
	v_cvt_pk_bf16_f32 v15, v16, v17
	v_add_f32_e32 v160, v160, v162
	v_cvt_pk_bf16_f32 v16, v10, v11
	v_cvt_pk_bf16_f32 v17, v12, v13
	global_store_dwordx4 v[250:251], v[14:17], off offset:256
	v_add_f32_e32 v2, v156, v160
	ds_bpermute_b32 v125, v132, v124
	ds_bpermute_b32 v101, v132, v100
	ds_bpermute_b32 v85, v132, v84
	ds_bpermute_b32 v45, v132, v44
	ds_bpermute_b32 v61, v132, v60
	ds_bpermute_b32 v37, v132, v36
	ds_bpermute_b32 v19, v132, v18
	ds_bpermute_b32 v3, v132, v2
	s_waitcnt lgkmcnt(0)
	v_add_f32_e32 v124, v124, v125
	v_add_f32_e32 v100, v100, v101
	v_add_f32_e32 v84, v84, v85
	v_add_f32_e32 v44, v44, v45
	v_add_f32_e32 v60, v60, v61
	v_add_f32_e32 v36, v36, v37
	v_add_f32_e32 v18, v18, v19
	v_add_f32_e32 v2, v2, v3
	ds_bpermute_b32 v125, v133, v124
	ds_bpermute_b32 v101, v133, v100
	ds_bpermute_b32 v85, v133, v84
	ds_bpermute_b32 v45, v133, v44
	ds_bpermute_b32 v61, v133, v60
	ds_bpermute_b32 v37, v133, v36
	ds_bpermute_b32 v19, v133, v18
	ds_bpermute_b32 v3, v133, v2
	s_and_saveexec_b64 s[0:1], s[4:5]
	s_cbranch_execz .LBB0_1059
	s_waitcnt lgkmcnt(0)
	v_add_f32_e32 v124, v124, v125
	v_add_f32_e32 v100, v100, v101
	v_add_f32_e32 v84, v84, v85
	v_add_f32_e32 v44, v44, v45
	v_add_f32_e32 v60, v60, v61
	v_add_f32_e32 v36, v36, v37
	v_add_f32_e32 v18, v18, v19
	v_add_f32_e32 v2, v2, v3
	global_atomic_add_f32 v[252:253], v124, off
	global_atomic_add_f32 v[252:253], v100, off offset:64
	global_atomic_add_f32 v[252:253], v84, off offset:128
	global_atomic_add_f32 v[252:253], v44, off offset:192
	global_atomic_add_f32 v[252:253], v60, off offset:512
	global_atomic_add_f32 v[252:253], v36, off offset:576
	global_atomic_add_f32 v[252:253], v18, off offset:640
	global_atomic_add_f32 v[252:253], v2, off offset:704
